# P0 wf staging loads batched + GEMM SP1 mid-segment lgkmcnt(0) relaxed to counted wait
# baseline (speedup 1.0000x reference)
; #define PG8_STAGE(bufoff, gbase, voff) do { const char* gb_ = (const char*)(gbase); asm volatile("" : "+s"(gb_)); _Pragma("unroll") for (int _i = 0; _i < 2; ++_i) { unsigned vo_ = (voff)[_i]; asm volatile("" : "+v"(vo_)); \
;         __builtin_amdgcn_global_load_lds((const unsigned*)(gb_ + vo_), (PG8_LAS unsigned*)(lds + (bufoff) + ldsw + _i * 8192), 16, 0, 0); } } while (0)
; #define PG8_LDA(dst, b, h) do { _Pragma("unroll") for (int m = 0; m < 4; ++m) _Pragma("unroll") for (int k = 0; k < 2; ++k) dst[m][k] = *(const PG8_LAS bf16x8*)(lds + PG8_SA(b, h) + aoff + m * 2048 + k * 1024); } while (0)
; #define PG8_LDB(dst, b, h) do { _Pragma("unroll") for (int n = 0; n < 2; ++n) _Pragma("unroll") for (int k = 0; k < 2; ++k) dst[n][k] = *(const PG8_LAS bf16x8*)(lds + PG8_SB(b, h) + boff + n * 2048 + k * 1024); } while (0)
; #define PG8_MMA(ai, bj, At, Bt) do { __builtin_amdgcn_s_setprio(1); _Pragma("unroll") for (int m = 0; m < 4; ++m) _Pragma("unroll") for (int n = 0; n < 2; ++n) _Pragma("unroll") for (int k = 0; k < 2; ++k) \
;         acc[ai][bj][m][n] = __builtin_amdgcn_mfma_f32_16x16x32_bf16(Bt[n][k], At[m][k], acc[ai][bj][m][n], 0, 0, 0); __builtin_amdgcn_s_setprio(0); } while (0)
; #define PG8_WAIT_V(n) asm volatile("s_waitcnt vmcnt(" #n ")" ::: "memory")
; #define PG8_WAIT_L(n) asm volatile("s_waitcnt lgkmcnt(" #n ")" ::: "memory")
; #define PG8_BAR __builtin_amdgcn_s_barrier()
; #define PG8_SCHED __builtin_amdgcn_sched_barrier(0)
;     ...
;             const char* a1 = cA + (size_t)(t + 1) * kstep;
;             const char* a2 = last ? nA : cA + (size_t)(t + 2) * kstep; const char* b2 = last ? nB : cB + (size_t)(t + 2) * kstep;
;             const char* a3 = a2 + kstep; const char* b3 = b2 + kstep;
;             if (last && has_next) S.a_ready(nxt);
;             if constexpr (SP2) {
;             PG8_LDB(B0, 0, 0); PG8_LDB(B1, 0, 1); PG8_SCHED; PG8_LDA(At, 0, 0); PG8_STAGE(PG8_SA(1, 1), a1 + hstep, voffA);
;             PG8_WAIT_V(8); PG8_WAIT_L(0); PG8_BAR; PG8_MMA(0, 0, At, B0); PG8_MMA(0, 1, At, B1); PG8_BAR; PG8_SCHED;
;             PG8_LDA(At, 0, 1); PG8_STAGE(PG8_SB(0, 0), b2, voffB); PG8_STAGE(PG8_SB(0, 1), b2 + hstepB, voffB); PG8_STAGE(PG8_SA(0, 0), a2, voffA);
.LBB0_578:
	v_add_u32_e32 v142, s42, v211
	v_add_u32_e32 v158, s43, v211
	ds_read_b128 v[130:133], v142
	ds_read_b128 v[134:137], v142 offset:1024
	ds_read_b128 v[138:141], v142 offset:2048
	ds_read_b128 v[142:145], v142 offset:3072
	ds_read_b128 v[146:149], v158
	ds_read_b128 v[150:153], v158 offset:1024
	ds_read_b128 v[154:157], v158 offset:2048
	ds_read_b128 v[158:161], v158 offset:3072
	s_add_u32 s22, s20, 0x100
	s_addc_u32 s23, s21, 0
	s_cmp_eq_u32 s13, 4
	s_cselect_b32 s28, s16, s22
	s_cselect_b32 s29, s17, s23
	s_cselect_b32 s26, s5, s7
	s_cselect_b32 s27, s3, s11
	s_add_u32 s24, s28, 0x80
	s_addc_u32 s25, s29, 0
	s_add_u32 s20, s20, 0x20080
	s_addc_u32 s21, s21, 0
	v_mov_b32_e32 v196, v1
	ds_read_b128 v[162:165], v212
	ds_read_b128 v[166:169], v212 offset:1024
	ds_read_b128 v[170:173], v212 offset:2048
	s_waitcnt lgkmcnt(10)
	ds_read_b128 v[174:177], v212 offset:3072
	ds_read_b128 v[178:181], v212 offset:4096
	ds_read_b128 v[182:185], v212 offset:5120
	ds_read_b128 v[186:189], v212 offset:6144
	ds_read_b128 v[190:193], v212 offset:7168
	s_add_i32 m0, s31, 0xc000
	s_nop 0
	global_load_lds_dwordx4 v196, s[20:21]
	v_mov_b32_e32 v196, v208
	s_add_i32 m0, s31, 0xe000
	s_nop 0
	global_load_lds_dwordx4 v196, s[20:21]
	s_waitcnt vmcnt(8)
	s_waitcnt lgkmcnt(0)
	s_barrier
	s_setprio 1
	v_mfma_f32_16x16x32_bf16 v[126:129], v[130:133], v[162:165], v[126:129]
	v_mfma_f32_16x16x32_bf16 v[122:125], v[138:141], v[162:165], v[122:125]
	v_mfma_f32_16x16x32_bf16 v[118:121], v[130:133], v[170:173], v[118:121]
	v_mfma_f32_16x16x32_bf16 v[114:117], v[138:141], v[170:173], v[114:117]
	s_waitcnt lgkmcnt(0)
	v_mfma_f32_16x16x32_bf16 v[110:113], v[130:133], v[178:181], v[110:113]
	v_mfma_f32_16x16x32_bf16 v[106:109], v[138:141], v[178:181], v[106:109]
	v_mfma_f32_16x16x32_bf16 v[102:105], v[130:133], v[186:189], v[102:105]
	v_mfma_f32_16x16x32_bf16 v[98:101], v[138:141], v[186:189], v[98:101]
	v_mfma_f32_16x16x32_bf16 v[126:129], v[134:137], v[166:169], v[126:129]
	v_mfma_f32_16x16x32_bf16 v[122:125], v[142:145], v[166:169], v[122:125]
	v_mfma_f32_16x16x32_bf16 v[118:121], v[134:137], v[174:177], v[118:121]
	v_mfma_f32_16x16x32_bf16 v[114:117], v[142:145], v[174:177], v[114:117]
	v_mfma_f32_16x16x32_bf16 v[110:113], v[134:137], v[182:185], v[110:113]
	v_mfma_f32_16x16x32_bf16 v[106:109], v[142:145], v[182:185], v[106:109]
	v_mfma_f32_16x16x32_bf16 v[102:105], v[134:137], v[190:193], v[102:105]
	v_mfma_f32_16x16x32_bf16 v[98:101], v[142:145], v[190:193], v[98:101]
	s_setprio 0
	s_setprio 1
	v_mfma_f32_16x16x32_bf16 v[94:97], v[146:149], v[162:165], v[94:97]
	v_mfma_f32_16x16x32_bf16 v[90:93], v[154:157], v[162:165], v[90:93]
	v_mfma_f32_16x16x32_bf16 v[86:89], v[146:149], v[170:173], v[86:89]
	v_mfma_f32_16x16x32_bf16 v[82:85], v[154:157], v[170:173], v[82:85]
	v_mfma_f32_16x16x32_bf16 v[78:81], v[146:149], v[178:181], v[78:81]
	v_mfma_f32_16x16x32_bf16 v[74:77], v[154:157], v[178:181], v[74:77]
	v_mfma_f32_16x16x32_bf16 v[70:73], v[146:149], v[186:189], v[70:73]
	v_mfma_f32_16x16x32_bf16 v[62:65], v[154:157], v[186:189], v[62:65]
	v_mfma_f32_16x16x32_bf16 v[94:97], v[150:153], v[166:169], v[94:97]
	v_mfma_f32_16x16x32_bf16 v[90:93], v[158:161], v[166:169], v[90:93]
	v_mfma_f32_16x16x32_bf16 v[86:89], v[150:153], v[174:177], v[86:89]
	v_mfma_f32_16x16x32_bf16 v[82:85], v[158:161], v[174:177], v[82:85]
	v_mfma_f32_16x16x32_bf16 v[78:81], v[150:153], v[182:185], v[78:81]
	v_mfma_f32_16x16x32_bf16 v[74:77], v[158:161], v[182:185], v[74:77]
	v_mfma_f32_16x16x32_bf16 v[70:73], v[150:153], v[190:193], v[70:73]
	v_mfma_f32_16x16x32_bf16 v[62:65], v[158:161], v[190:193], v[62:65]
	s_setprio 0
	s_barrier
	s_mov_b64 s[20:21], s[26:27]
	v_mov_b32_e32 v196, v195
	s_add_i32 s15, s42, s30
	ds_read_b128 v[162:165], v212 offset:16384
	ds_read_b128 v[166:169], v212 offset:17408
	ds_read_b128 v[170:173], v212 offset:18432
	ds_read_b128 v[174:177], v212 offset:19456
	ds_read_b128 v[178:181], v212 offset:20480
	ds_read_b128 v[182:185], v212 offset:21504
	ds_read_b128 v[186:189], v212 offset:22528
	ds_read_b128 v[190:193], v212 offset:23552
	s_mov_b32 m0, s15
	s_nop 0
	global_load_lds_dwordx4 v196, s[20:21]
	v_mov_b32_e32 v196, v209
	s_add_i32 m0, s15, 0x2000
	s_nop 0
	global_load_lds_dwordx4 v196, s[20:21]
	s_add_u32 s20, s26, 0x20000
	s_addc_u32 s21, s27, 0
	v_mov_b32_e32 v196, v195
	s_add_i32 s15, s43, s30
	s_mov_b32 m0, s15
	s_nop 0
	global_load_lds_dwordx4 v196, s[20:21]
	v_mov_b32_e32 v196, v209
	s_add_i32 m0, s15, 0x2000
	s_nop 0
	global_load_lds_dwordx4 v196, s[20:21]
	s_mov_b64 s[20:21], s[28:29]
	v_mov_b32_e32 v196, v1
	s_mov_b32 m0, s31
	s_nop 0
	global_load_lds_dwordx4 v196, s[20:21]
	v_mov_b32_e32 v196, v208
	s_mov_b32 m0, s33
	s_nop 0
	global_load_lds_dwordx4 v196, s[20:21]
	s_waitcnt vmcnt(8)
	s_waitcnt lgkmcnt(0)
	s_barrier
; #define PG8_STAGE(bufoff, gbase, voff) do { const char* gb_ = (const char*)(gbase); asm volatile("" : "+s"(gb_)); _Pragma("unroll") for (int _i = 0; _i < 2; ++_i) { unsigned vo_ = (voff)[_i]; asm volatile("" : "+v"(vo_)); \
;         __builtin_amdgcn_global_load_lds((const unsigned*)(gb_ + vo_), (PG8_LAS unsigned*)(lds + (bufoff) + ldsw + _i * 8192), 16, 0, 0); } } while (0)
; #define PG8_LDA(dst, b, h) do { _Pragma("unroll") for (int m = 0; m < 4; ++m) _Pragma("unroll") for (int k = 0; k < 2; ++k) dst[m][k] = *(const PG8_LAS bf16x8*)(lds + PG8_SA(b, h) + aoff + m * 2048 + k * 1024); } while (0)
; #define PG8_LDB(dst, b, h) do { _Pragma("unroll") for (int n = 0; n < 2; ++n) _Pragma("unroll") for (int k = 0; k < 2; ++k) dst[n][k] = *(const PG8_LAS bf16x8*)(lds + PG8_SB(b, h) + boff + n * 2048 + k * 1024); } while (0)
; #define PG8_MMA(ai, bj, At, Bt) do { __builtin_amdgcn_s_setprio(1); _Pragma("unroll") for (int m = 0; m < 4; ++m) _Pragma("unroll") for (int n = 0; n < 2; ++n) _Pragma("unroll") for (int k = 0; k < 2; ++k) \
;         acc[ai][bj][m][n] = __builtin_amdgcn_mfma_f32_16x16x32_bf16(Bt[n][k], At[m][k], acc[ai][bj][m][n], 0, 0, 0); __builtin_amdgcn_s_setprio(0); } while (0)
; #define PG8_WAIT_V(n) asm volatile("s_waitcnt vmcnt(" #n ")" ::: "memory")
; #define PG8_WAIT_L(n) asm volatile("s_waitcnt lgkmcnt(" #n ")" ::: "memory")
; #define PG8_BAR __builtin_amdgcn_s_barrier()
; #define PG8_SCHED __builtin_amdgcn_sched_barrier(0)
;     ...
;             PG8_WAIT_V(8); PG8_WAIT_L(0); PG8_BAR; PG8_MMA(1, 0, At, B0); PG8_MMA(1, 1, At, B1); PG8_BAR; PG8_SCHED;
;             PG8_LDB(B0, 1, 0); PG8_LDB(B1, 1, 1); PG8_SCHED; PG8_LDA(At, 1, 0); PG8_STAGE(PG8_SA(0, 1), a2 + hstep, voffA);
;             PG8_WAIT_V(8); PG8_WAIT_L(0); PG8_BAR; PG8_MMA(0, 0, At, B0); PG8_MMA(0, 1, At, B1); PG8_BAR; PG8_SCHED;
	s_setprio 1
	s_waitcnt lgkmcnt(0)
	v_mfma_f32_16x16x32_bf16 v[66:69], v[130:133], v[162:165], v[66:69]
	v_mfma_f32_16x16x32_bf16 v[58:61], v[138:141], v[162:165], v[58:61]
	v_mfma_f32_16x16x32_bf16 v[54:57], v[130:133], v[170:173], v[54:57]
	v_mfma_f32_16x16x32_bf16 v[50:53], v[138:141], v[170:173], v[50:53]
	v_mfma_f32_16x16x32_bf16 v[46:49], v[130:133], v[178:181], v[46:49]
	v_mfma_f32_16x16x32_bf16 v[42:45], v[138:141], v[178:181], v[42:45]
	v_mfma_f32_16x16x32_bf16 v[38:41], v[130:133], v[186:189], v[38:41]
	v_mfma_f32_16x16x32_bf16 v[34:37], v[138:141], v[186:189], v[34:37]
	v_mfma_f32_16x16x32_bf16 v[66:69], v[134:137], v[166:169], v[66:69]
	v_mfma_f32_16x16x32_bf16 v[58:61], v[142:145], v[166:169], v[58:61]
	v_mfma_f32_16x16x32_bf16 v[54:57], v[134:137], v[174:177], v[54:57]
	v_mfma_f32_16x16x32_bf16 v[50:53], v[142:145], v[174:177], v[50:53]
	v_mfma_f32_16x16x32_bf16 v[46:49], v[134:137], v[182:185], v[46:49]
	v_mfma_f32_16x16x32_bf16 v[42:45], v[142:145], v[182:185], v[42:45]
	v_mfma_f32_16x16x32_bf16 v[38:41], v[134:137], v[190:193], v[38:41]
	v_mfma_f32_16x16x32_bf16 v[34:37], v[142:145], v[190:193], v[34:37]
	s_setprio 0
	s_setprio 1
	v_mfma_f32_16x16x32_bf16 v[30:33], v[146:149], v[162:165], v[30:33]
	v_mfma_f32_16x16x32_bf16 v[26:29], v[154:157], v[162:165], v[26:29]
	v_mfma_f32_16x16x32_bf16 v[22:25], v[146:149], v[170:173], v[22:25]
	v_mfma_f32_16x16x32_bf16 v[18:21], v[154:157], v[170:173], v[18:21]
	v_mfma_f32_16x16x32_bf16 v[14:17], v[146:149], v[178:181], v[14:17]
	v_mfma_f32_16x16x32_bf16 v[10:13], v[154:157], v[178:181], v[10:13]
	v_mfma_f32_16x16x32_bf16 v[6:9], v[146:149], v[186:189], v[6:9]
	v_mfma_f32_16x16x32_bf16 v[2:5], v[154:157], v[186:189], v[2:5]
	v_mfma_f32_16x16x32_bf16 v[30:33], v[150:153], v[166:169], v[30:33]
	v_mfma_f32_16x16x32_bf16 v[26:29], v[158:161], v[166:169], v[26:29]
	v_mfma_f32_16x16x32_bf16 v[22:25], v[150:153], v[174:177], v[22:25]
	v_mfma_f32_16x16x32_bf16 v[18:21], v[158:161], v[174:177], v[18:21]
	v_mfma_f32_16x16x32_bf16 v[14:17], v[150:153], v[182:185], v[14:17]
	v_mfma_f32_16x16x32_bf16 v[10:13], v[158:161], v[182:185], v[10:13]
	v_mfma_f32_16x16x32_bf16 v[6:9], v[150:153], v[190:193], v[6:9]
	v_mfma_f32_16x16x32_bf16 v[2:5], v[158:161], v[190:193], v[2:5]
	s_setprio 0
	s_barrier
	s_add_i32 s15, 0, 0x18000
	s_add_i32 s46, 0, 0x1c000
	v_add_u32_e32 v142, s15, v211
	v_add_u32_e32 v158, s46, v211
	ds_read_b128 v[130:133], v142
	ds_read_b128 v[134:137], v142 offset:1024
	ds_read_b128 v[138:141], v142 offset:2048
	ds_read_b128 v[142:145], v142 offset:3072
	ds_read_b128 v[146:149], v158
	ds_read_b128 v[150:153], v158 offset:1024
	ds_read_b128 v[154:157], v158 offset:2048
	ds_read_b128 v[158:161], v158 offset:3072
	s_add_u32 s20, s28, 0x20000
	s_addc_u32 s21, s29, 0
	v_mov_b32_e32 v196, v1
	s_mov_b32 m0, s34
	ds_read_b128 v[162:165], v212 offset:32768
	ds_read_b128 v[166:169], v212 offset:33792
	ds_read_b128 v[170:173], v212 offset:34816
	ds_read_b128 v[174:177], v212 offset:35840
	ds_read_b128 v[178:181], v212 offset:36864
	ds_read_b128 v[182:185], v212 offset:37888
	ds_read_b128 v[186:189], v212 offset:38912
	ds_read_b128 v[190:193], v212 offset:39936
	s_nop 0
	global_load_lds_dwordx4 v196, s[20:21]
	v_mov_b32_e32 v196, v208
	s_mov_b32 m0, s35
	s_nop 0
	global_load_lds_dwordx4 v196, s[20:21]
	s_waitcnt vmcnt(8)
	s_waitcnt lgkmcnt(0)
	s_barrier
	s_setprio 1
	s_waitcnt lgkmcnt(0)
	v_mfma_f32_16x16x32_bf16 v[126:129], v[130:133], v[162:165], v[126:129]
	v_mfma_f32_16x16x32_bf16 v[122:125], v[138:141], v[162:165], v[122:125]
	v_mfma_f32_16x16x32_bf16 v[118:121], v[130:133], v[170:173], v[118:121]
	v_mfma_f32_16x16x32_bf16 v[114:117], v[138:141], v[170:173], v[114:117]
	v_mfma_f32_16x16x32_bf16 v[110:113], v[130:133], v[178:181], v[110:113]
	v_mfma_f32_16x16x32_bf16 v[106:109], v[138:141], v[178:181], v[106:109]
	v_mfma_f32_16x16x32_bf16 v[102:105], v[130:133], v[186:189], v[102:105]
	v_mfma_f32_16x16x32_bf16 v[98:101], v[138:141], v[186:189], v[98:101]
	v_mfma_f32_16x16x32_bf16 v[126:129], v[134:137], v[166:169], v[126:129]
	v_mfma_f32_16x16x32_bf16 v[122:125], v[142:145], v[166:169], v[122:125]
	v_mfma_f32_16x16x32_bf16 v[118:121], v[134:137], v[174:177], v[118:121]
	v_mfma_f32_16x16x32_bf16 v[114:117], v[142:145], v[174:177], v[114:117]
	v_mfma_f32_16x16x32_bf16 v[110:113], v[134:137], v[182:185], v[110:113]
	v_mfma_f32_16x16x32_bf16 v[106:109], v[142:145], v[182:185], v[106:109]
	v_mfma_f32_16x16x32_bf16 v[102:105], v[134:137], v[190:193], v[102:105]
	v_mfma_f32_16x16x32_bf16 v[98:101], v[142:145], v[190:193], v[98:101]
	s_setprio 0
	s_setprio 1
	v_mfma_f32_16x16x32_bf16 v[94:97], v[146:149], v[162:165], v[94:97]
	v_mfma_f32_16x16x32_bf16 v[90:93], v[154:157], v[162:165], v[90:93]
	v_mfma_f32_16x16x32_bf16 v[86:89], v[146:149], v[170:173], v[86:89]
	v_mfma_f32_16x16x32_bf16 v[82:85], v[154:157], v[170:173], v[82:85]
	v_mfma_f32_16x16x32_bf16 v[78:81], v[146:149], v[178:181], v[78:81]
	v_mfma_f32_16x16x32_bf16 v[74:77], v[154:157], v[178:181], v[74:77]
	v_mfma_f32_16x16x32_bf16 v[70:73], v[146:149], v[186:189], v[70:73]
	v_mfma_f32_16x16x32_bf16 v[62:65], v[154:157], v[186:189], v[62:65]
	v_mfma_f32_16x16x32_bf16 v[94:97], v[150:153], v[166:169], v[94:97]
	v_mfma_f32_16x16x32_bf16 v[90:93], v[158:161], v[166:169], v[90:93]
	v_mfma_f32_16x16x32_bf16 v[86:89], v[150:153], v[174:177], v[86:89]
	v_mfma_f32_16x16x32_bf16 v[82:85], v[158:161], v[174:177], v[82:85]
	v_mfma_f32_16x16x32_bf16 v[78:81], v[150:153], v[182:185], v[78:81]
	v_mfma_f32_16x16x32_bf16 v[74:77], v[158:161], v[182:185], v[74:77]
	v_mfma_f32_16x16x32_bf16 v[70:73], v[150:153], v[190:193], v[70:73]
	v_mfma_f32_16x16x32_bf16 v[62:65], v[158:161], v[190:193], v[62:65]
	s_setprio 0
	s_barrier
; #define PG8_STAGE(bufoff, gbase, voff) do { const char* gb_ = (const char*)(gbase); asm volatile("" : "+s"(gb_)); _Pragma("unroll") for (int _i = 0; _i < 2; ++_i) { unsigned vo_ = (voff)[_i]; asm volatile("" : "+v"(vo_)); \
;         __builtin_amdgcn_global_load_lds((const unsigned*)(gb_ + vo_), (PG8_LAS unsigned*)(lds + (bufoff) + ldsw + _i * 8192), 16, 0, 0); } } while (0)
; #define PG8_LDA(dst, b, h) do { _Pragma("unroll") for (int m = 0; m < 4; ++m) _Pragma("unroll") for (int k = 0; k < 2; ++k) dst[m][k] = *(const PG8_LAS bf16x8*)(lds + PG8_SA(b, h) + aoff + m * 2048 + k * 1024); } while (0)
; #define PG8_WAIT_V(n) asm volatile("s_waitcnt vmcnt(" #n ")" ::: "memory")
; #define PG8_WAIT_L(n) asm volatile("s_waitcnt lgkmcnt(" #n ")" ::: "memory")
;     ...
;             PG8_LDA(At, 1, 1); PG8_STAGE(PG8_SB(1, 0), b3, voffB); PG8_STAGE(PG8_SB(1, 1), b3 + hstepB, voffB); PG8_STAGE(PG8_SA(1, 0), a3, voffA);
;             PG8_WAIT_V(8); PG8_WAIT_L(0); PG8_BAR; PG8_MMA(1, 0, At, B0); PG8_MMA(1, 1, At, B1); PG8_BAR; PG8_SCHED;
;             } else {
;             PG8_LDB(B0, 0, 0); PG8_SCHED; PG8_LDA(At, 0, 0); PG8_STAGE(PG8_SA(1, 1), a1 + hstep, voffA);
;             PG8_WAIT_L(8); PG8_BAR; PG8_WAIT_L(0); PG8_MMA(0, 0, At, B0); PG8_BAR; PG8_SCHED;
;             PG8_LDB(B1, 0, 1); PG8_STAGE(PG8_SB(0, 0), b2, voffB);
;             PG8_BAR; PG8_WAIT_L(0); PG8_MMA(0, 1, At, B1); PG8_BAR;
;             PG8_LDA(At, 0, 1); PG8_STAGE(PG8_SA(0, 0), a2, voffA);
;             PG8_BAR; PG8_WAIT_L(0); PG8_MMA(1, 0, At, B0); PG8_BAR; PG8_SCHED;
;             PG8_STAGE(PG8_SB(0, 1), b2 + hstepB, voffB);
;             PG8_WAIT_V(6); PG8_BAR; PG8_MMA(1, 1, At, B1); PG8_BAR;
;             PG8_LDB(B0, 1, 0); PG8_SCHED; PG8_LDA(At, 1, 0); PG8_STAGE(PG8_SA(0, 1), a2 + hstep, voffA);
;             PG8_WAIT_L(8); PG8_BAR; PG8_WAIT_L(0); PG8_MMA(0, 0, At, B0); PG8_BAR; PG8_SCHED;
;             PG8_LDB(B1, 1, 1); PG8_STAGE(PG8_SB(1, 0), b3, voffB);
;             PG8_BAR; PG8_WAIT_L(0); PG8_MMA(0, 1, At, B1); PG8_BAR;
;             PG8_LDA(At, 1, 1); PG8_STAGE(PG8_SA(1, 0), a3, voffA);
;             PG8_BAR; PG8_WAIT_L(0); PG8_MMA(1, 0, At, B0); PG8_BAR; PG8_SCHED;
;             PG8_STAGE(PG8_SB(1, 1), b3 + hstepB, voffB);
;             PG8_WAIT_V(6); PG8_BAR; PG8_MMA(1, 1, At, B1); PG8_BAR;
;             }
;         }
;         if constexpr (ALIGN_EPI) { if (wr == 0) PG8_BAR; }
	s_add_u32 s20, s26, 0x80
	s_addc_u32 s21, s27, 0
	v_mov_b32_e32 v196, v195
	s_add_i32 s15, s15, s30
	ds_read_b128 v[162:165], v212 offset:49152
	ds_read_b128 v[166:169], v212 offset:50176
	ds_read_b128 v[170:173], v212 offset:51200
	ds_read_b128 v[174:177], v212 offset:52224
	ds_read_b128 v[178:181], v212 offset:53248
	ds_read_b128 v[182:185], v212 offset:54272
	ds_read_b128 v[186:189], v212 offset:55296
	ds_read_b128 v[190:193], v212 offset:56320
	s_mov_b32 m0, s15
	s_nop 0
	global_load_lds_dwordx4 v196, s[20:21]
	v_mov_b32_e32 v196, v209
	s_add_i32 m0, s15, 0x2000
	s_nop 0
	global_load_lds_dwordx4 v196, s[20:21]
	s_add_u32 s20, s26, 0x20080
	s_addc_u32 s21, s27, 0
	v_mov_b32_e32 v196, v195
	s_add_i32 s15, s46, s30
	s_mov_b32 m0, s15
	s_nop 0
	global_load_lds_dwordx4 v196, s[20:21]
	v_mov_b32_e32 v196, v209
	s_add_i32 m0, s15, 0x2000
	s_nop 0
	global_load_lds_dwordx4 v196, s[20:21]
	v_mov_b32_e32 v196, v1
	s_mov_b32 m0, s36
	s_nop 0
	global_load_lds_dwordx4 v196, s[24:25]
	v_mov_b32_e32 v196, v208
	s_mov_b32 m0, s37
	s_nop 0
	global_load_lds_dwordx4 v196, s[24:25]
	s_waitcnt vmcnt(8)
	s_waitcnt lgkmcnt(0)
	s_barrier
	s_setprio 1
	s_waitcnt lgkmcnt(0)
	v_mfma_f32_16x16x32_bf16 v[66:69], v[130:133], v[162:165], v[66:69]
	v_mfma_f32_16x16x32_bf16 v[58:61], v[138:141], v[162:165], v[58:61]
	v_mfma_f32_16x16x32_bf16 v[54:57], v[130:133], v[170:173], v[54:57]
	v_mfma_f32_16x16x32_bf16 v[50:53], v[138:141], v[170:173], v[50:53]
	v_mfma_f32_16x16x32_bf16 v[46:49], v[130:133], v[178:181], v[46:49]
	v_mfma_f32_16x16x32_bf16 v[42:45], v[138:141], v[178:181], v[42:45]
	v_mfma_f32_16x16x32_bf16 v[38:41], v[130:133], v[186:189], v[38:41]
	v_mfma_f32_16x16x32_bf16 v[34:37], v[138:141], v[186:189], v[34:37]
	v_mfma_f32_16x16x32_bf16 v[66:69], v[134:137], v[166:169], v[66:69]
	v_mfma_f32_16x16x32_bf16 v[58:61], v[142:145], v[166:169], v[58:61]
	v_mfma_f32_16x16x32_bf16 v[54:57], v[134:137], v[174:177], v[54:57]
	v_mfma_f32_16x16x32_bf16 v[50:53], v[142:145], v[174:177], v[50:53]
	v_mfma_f32_16x16x32_bf16 v[46:49], v[134:137], v[182:185], v[46:49]
	v_mfma_f32_16x16x32_bf16 v[42:45], v[142:145], v[182:185], v[42:45]
	v_mfma_f32_16x16x32_bf16 v[38:41], v[134:137], v[190:193], v[38:41]
	v_mfma_f32_16x16x32_bf16 v[34:37], v[142:145], v[190:193], v[34:37]
	s_setprio 0
	s_setprio 1
	v_mfma_f32_16x16x32_bf16 v[30:33], v[146:149], v[162:165], v[30:33]
	v_mfma_f32_16x16x32_bf16 v[26:29], v[154:157], v[162:165], v[26:29]
	v_mfma_f32_16x16x32_bf16 v[22:25], v[146:149], v[170:173], v[22:25]
	v_mfma_f32_16x16x32_bf16 v[18:21], v[154:157], v[170:173], v[18:21]
	v_mfma_f32_16x16x32_bf16 v[14:17], v[146:149], v[178:181], v[14:17]
	v_mfma_f32_16x16x32_bf16 v[10:13], v[154:157], v[178:181], v[10:13]
	v_mfma_f32_16x16x32_bf16 v[6:9], v[146:149], v[186:189], v[6:9]
	v_mfma_f32_16x16x32_bf16 v[2:5], v[154:157], v[186:189], v[2:5]
	v_mfma_f32_16x16x32_bf16 v[30:33], v[150:153], v[166:169], v[30:33]
	v_mfma_f32_16x16x32_bf16 v[26:29], v[158:161], v[166:169], v[26:29]
	v_mfma_f32_16x16x32_bf16 v[22:25], v[150:153], v[174:177], v[22:25]
	v_mfma_f32_16x16x32_bf16 v[18:21], v[158:161], v[174:177], v[18:21]
	v_mfma_f32_16x16x32_bf16 v[14:17], v[150:153], v[182:185], v[14:17]
	v_mfma_f32_16x16x32_bf16 v[10:13], v[158:161], v[182:185], v[10:13]
	v_mfma_f32_16x16x32_bf16 v[6:9], v[150:153], v[190:193], v[6:9]
	v_mfma_f32_16x16x32_bf16 v[2:5], v[158:161], v[190:193], v[2:5]
	s_setprio 0
	s_barrier
	s_add_i32 s13, s13, 2
	s_add_u32 s7, s7, 0x100
	s_addc_u32 s11, s11, 0
	s_cmp_gt_u32 s13, 5
	s_mov_b64 s[20:21], s[22:23]
	s_cbranch_scc0 .LBB0_578
	s_and_b64 vcc, exec, s[8:9]
	s_cbranch_vccz .LBB0_581
	s_barrier

; #define PG8_STAGE(bufoff, gbase, voff) do { const char* gb_ = (const char*)(gbase); asm volatile("" : "+s"(gb_)); _Pragma("unroll") for (int _i = 0; _i < 2; ++_i) { unsigned vo_ = (voff)[_i]; asm volatile("" : "+v"(vo_)); \
;         __builtin_amdgcn_global_load_lds((const unsigned*)(gb_ + vo_), (PG8_LAS unsigned*)(lds + (bufoff) + ldsw + _i * 8192), 16, 0, 0); } } while (0)
; #define PG8_LDA(dst, b, h) do { _Pragma("unroll") for (int m = 0; m < 4; ++m) _Pragma("unroll") for (int k = 0; k < 2; ++k) dst[m][k] = *(const PG8_LAS bf16x8*)(lds + PG8_SA(b, h) + aoff + m * 2048 + k * 1024); } while (0)
; #define PG8_LDB(dst, b, h) do { _Pragma("unroll") for (int n = 0; n < 2; ++n) _Pragma("unroll") for (int k = 0; k < 2; ++k) dst[n][k] = *(const PG8_LAS bf16x8*)(lds + PG8_SB(b, h) + boff + n * 2048 + k * 1024); } while (0)
; #define PG8_MMA(ai, bj, At, Bt) do { __builtin_amdgcn_s_setprio(1); _Pragma("unroll") for (int m = 0; m < 4; ++m) _Pragma("unroll") for (int n = 0; n < 2; ++n) _Pragma("unroll") for (int k = 0; k < 2; ++k) \
;         acc[ai][bj][m][n] = __builtin_amdgcn_mfma_f32_16x16x32_bf16(Bt[n][k], At[m][k], acc[ai][bj][m][n], 0, 0, 0); __builtin_amdgcn_s_setprio(0); } while (0)
; #define PG8_WAIT_V(n) asm volatile("s_waitcnt vmcnt(" #n ")" ::: "memory")
; #define PG8_WAIT_L(n) asm volatile("s_waitcnt lgkmcnt(" #n ")" ::: "memory")
; #define PG8_BAR __builtin_amdgcn_s_barrier()
; #define PG8_SCHED __builtin_amdgcn_sched_barrier(0)
;     ...
;         for (int t = 0; t < nt; t += 2) {
;             const bool last = (t == nt - 2);
;             if (GP && t == 2) gp1 = __builtin_amdgcn_s_memrealtime();
;             const char* a1 = cA + (size_t)(t + 1) * kstep;
;             const char* a2 = last ? nA : cA + (size_t)(t + 2) * kstep; const char* b2 = last ? nB : cB + (size_t)(t + 2) * kstep;
;             const char* a3 = a2 + kstep; const char* b3 = b2 + kstep;
;             if (last && has_next) S.a_ready(nxt);
;             if constexpr (SP2) {
;             PG8_LDB(B0, 0, 0); PG8_LDB(B1, 0, 1); PG8_SCHED; PG8_LDA(At, 0, 0); PG8_STAGE(PG8_SA(1, 1), a1 + hstep, voffA);
;             PG8_WAIT_V(8); PG8_WAIT_L(0); PG8_BAR; PG8_MMA(0, 0, At, B0); PG8_MMA(0, 1, At, B1); PG8_BAR; PG8_SCHED;
;             PG8_LDA(At, 0, 1); PG8_STAGE(PG8_SB(0, 0), b2, voffB); PG8_STAGE(PG8_SB(0, 1), b2 + hstepB, voffB); PG8_STAGE(PG8_SA(0, 0), a2, voffA);
.LBB0_799:
	s_add_u32 s46, s14, s22
	s_addc_u32 s47, s15, s23
	s_add_u32 s24, s46, 0x100
	s_addc_u32 s25, s47, 0
	v_add_u32_e32 v154, s40, v140
	v_add_u32_e32 v170, s41, v140
	s_add_u32 s26, s12, s22
	ds_read_b128 v[142:145], v154
	ds_read_b128 v[146:149], v154 offset:1024
	ds_read_b128 v[150:153], v154 offset:2048
	ds_read_b128 v[154:157], v154 offset:3072
	ds_read_b128 v[158:161], v170
	ds_read_b128 v[162:165], v170 offset:1024
	ds_read_b128 v[166:169], v170 offset:2048
	ds_read_b128 v[170:173], v170 offset:3072
	s_addc_u32 s27, s13, s23
	s_add_u32 s26, s26, 0x100
	s_addc_u32 s27, s27, 0
	s_cmp_eq_u32 s45, 12
	s_cselect_b32 s28, s43, s24
	s_cselect_b32 s29, s19, s25
	s_cselect_b32 s26, s44, s26
	s_cselect_b32 s27, s17, s27
	s_add_u32 s24, s28, 0x80
	s_addc_u32 s25, s29, 0
	s_add_u32 s46, s46, 0x40080
	s_addc_u32 s47, s47, 0
	v_mov_b32_e32 v206, v135
	s_waitcnt lgkmcnt(7)
	ds_read_b128 v[174:177], v141
	ds_read_b128 v[178:181], v141 offset:1024
	ds_read_b128 v[182:185], v141 offset:2048
	ds_read_b128 v[186:189], v141 offset:3072
	ds_read_b128 v[190:193], v141 offset:4096
	ds_read_b128 v[194:197], v141 offset:5120
	ds_read_b128 v[198:201], v141 offset:6144
	ds_read_b128 v[202:205], v141 offset:7168
	s_add_i32 m0, s33, 0xc000
	s_nop 0
	global_load_lds_dwordx4 v206, s[46:47]
	v_mov_b32_e32 v206, v137
	s_add_i32 m0, s33, 0xe000
	s_nop 0
	global_load_lds_dwordx4 v206, s[46:47]
	s_waitcnt vmcnt(8)
	s_waitcnt lgkmcnt(0)
	s_barrier
	s_setprio 1
	s_waitcnt lgkmcnt(0)
	v_mfma_f32_16x16x32_bf16 v[126:129], v[142:145], v[174:177], v[126:129]
	v_mfma_f32_16x16x32_bf16 v[122:125], v[150:153], v[174:177], v[122:125]
	v_mfma_f32_16x16x32_bf16 v[110:113], v[142:145], v[182:185], v[110:113]
	v_mfma_f32_16x16x32_bf16 v[106:109], v[150:153], v[182:185], v[106:109]
	v_mfma_f32_16x16x32_bf16 v[94:97], v[142:145], v[190:193], v[94:97]
	v_mfma_f32_16x16x32_bf16 v[90:93], v[150:153], v[190:193], v[90:93]
	v_mfma_f32_16x16x32_bf16 v[78:81], v[142:145], v[198:201], v[78:81]
	v_mfma_f32_16x16x32_bf16 v[74:77], v[150:153], v[198:201], v[74:77]
	v_mfma_f32_16x16x32_bf16 v[126:129], v[146:149], v[178:181], v[126:129]
	v_mfma_f32_16x16x32_bf16 v[122:125], v[154:157], v[178:181], v[122:125]
	v_mfma_f32_16x16x32_bf16 v[110:113], v[146:149], v[186:189], v[110:113]
	v_mfma_f32_16x16x32_bf16 v[106:109], v[154:157], v[186:189], v[106:109]
	v_mfma_f32_16x16x32_bf16 v[94:97], v[146:149], v[194:197], v[94:97]
	v_mfma_f32_16x16x32_bf16 v[90:93], v[154:157], v[194:197], v[90:93]
	v_mfma_f32_16x16x32_bf16 v[78:81], v[146:149], v[202:205], v[78:81]
	v_mfma_f32_16x16x32_bf16 v[74:77], v[154:157], v[202:205], v[74:77]
	s_setprio 0
	s_setprio 1
	v_mfma_f32_16x16x32_bf16 v[118:121], v[158:161], v[174:177], v[118:121]
	v_mfma_f32_16x16x32_bf16 v[114:117], v[166:169], v[174:177], v[114:117]
	v_mfma_f32_16x16x32_bf16 v[102:105], v[158:161], v[182:185], v[102:105]
	v_mfma_f32_16x16x32_bf16 v[98:101], v[166:169], v[182:185], v[98:101]
	v_mfma_f32_16x16x32_bf16 v[86:89], v[158:161], v[190:193], v[86:89]
	v_mfma_f32_16x16x32_bf16 v[82:85], v[166:169], v[190:193], v[82:85]
	v_mfma_f32_16x16x32_bf16 v[70:73], v[158:161], v[198:201], v[70:73]
	v_mfma_f32_16x16x32_bf16 v[66:69], v[166:169], v[198:201], v[66:69]
	v_mfma_f32_16x16x32_bf16 v[118:121], v[162:165], v[178:181], v[118:121]
	v_mfma_f32_16x16x32_bf16 v[114:117], v[170:173], v[178:181], v[114:117]
	v_mfma_f32_16x16x32_bf16 v[102:105], v[162:165], v[186:189], v[102:105]
	v_mfma_f32_16x16x32_bf16 v[98:101], v[170:173], v[186:189], v[98:101]
	v_mfma_f32_16x16x32_bf16 v[86:89], v[162:165], v[194:197], v[86:89]
	v_mfma_f32_16x16x32_bf16 v[82:85], v[170:173], v[194:197], v[82:85]
	v_mfma_f32_16x16x32_bf16 v[70:73], v[162:165], v[202:205], v[70:73]
	v_mfma_f32_16x16x32_bf16 v[66:69], v[170:173], v[202:205], v[66:69]
	s_setprio 0
	s_barrier
	s_mov_b64 s[46:47], s[26:27]
	v_mov_b32_e32 v206, v136
	s_add_i32 s48, s40, s1
	ds_read_b128 v[174:177], v141 offset:16384
	ds_read_b128 v[178:181], v141 offset:17408
	ds_read_b128 v[182:185], v141 offset:18432
	ds_read_b128 v[186:189], v141 offset:19456
	ds_read_b128 v[190:193], v141 offset:20480
	ds_read_b128 v[194:197], v141 offset:21504
	ds_read_b128 v[198:201], v141 offset:22528
	ds_read_b128 v[202:205], v141 offset:23552
	s_mov_b32 m0, s48
	s_nop 0
	global_load_lds_dwordx4 v206, s[46:47]
	v_mov_b32_e32 v206, v138
	s_add_i32 m0, s48, 0x2000
	s_nop 0
	global_load_lds_dwordx4 v206, s[46:47]
	s_add_u32 s46, s26, 0x40000
	s_addc_u32 s47, s27, 0
	v_mov_b32_e32 v206, v136
	s_add_i32 s48, s41, s1
	s_mov_b32 m0, s48
	s_nop 0
	global_load_lds_dwordx4 v206, s[46:47]
	v_mov_b32_e32 v206, v138
	s_add_i32 m0, s48, 0x2000
	s_nop 0
	global_load_lds_dwordx4 v206, s[46:47]
	s_mov_b64 s[46:47], s[28:29]
	v_mov_b32_e32 v206, v135
	s_mov_b32 m0, s33
	s_nop 0
	global_load_lds_dwordx4 v206, s[46:47]
	v_mov_b32_e32 v206, v137
	s_mov_b32 m0, s34
	s_nop 0
	global_load_lds_dwordx4 v206, s[46:47]
	s_waitcnt vmcnt(8)
	s_waitcnt lgkmcnt(0)
	s_barrier
; #define PG8_STAGE(bufoff, gbase, voff) do { const char* gb_ = (const char*)(gbase); asm volatile("" : "+s"(gb_)); _Pragma("unroll") for (int _i = 0; _i < 2; ++_i) { unsigned vo_ = (voff)[_i]; asm volatile("" : "+v"(vo_)); \
;         __builtin_amdgcn_global_load_lds((const unsigned*)(gb_ + vo_), (PG8_LAS unsigned*)(lds + (bufoff) + ldsw + _i * 8192), 16, 0, 0); } } while (0)
; #define PG8_LDA(dst, b, h) do { _Pragma("unroll") for (int m = 0; m < 4; ++m) _Pragma("unroll") for (int k = 0; k < 2; ++k) dst[m][k] = *(const PG8_LAS bf16x8*)(lds + PG8_SA(b, h) + aoff + m * 2048 + k * 1024); } while (0)
; #define PG8_LDB(dst, b, h) do { _Pragma("unroll") for (int n = 0; n < 2; ++n) _Pragma("unroll") for (int k = 0; k < 2; ++k) dst[n][k] = *(const PG8_LAS bf16x8*)(lds + PG8_SB(b, h) + boff + n * 2048 + k * 1024); } while (0)
; #define PG8_MMA(ai, bj, At, Bt) do { __builtin_amdgcn_s_setprio(1); _Pragma("unroll") for (int m = 0; m < 4; ++m) _Pragma("unroll") for (int n = 0; n < 2; ++n) _Pragma("unroll") for (int k = 0; k < 2; ++k) \
;         acc[ai][bj][m][n] = __builtin_amdgcn_mfma_f32_16x16x32_bf16(Bt[n][k], At[m][k], acc[ai][bj][m][n], 0, 0, 0); __builtin_amdgcn_s_setprio(0); } while (0)
; #define PG8_WAIT_V(n) asm volatile("s_waitcnt vmcnt(" #n ")" ::: "memory")
; #define PG8_WAIT_L(n) asm volatile("s_waitcnt lgkmcnt(" #n ")" ::: "memory")
; #define PG8_BAR __builtin_amdgcn_s_barrier()
; #define PG8_SCHED __builtin_amdgcn_sched_barrier(0)
;     ...
;             PG8_WAIT_V(8); PG8_WAIT_L(0); PG8_BAR; PG8_MMA(1, 0, At, B0); PG8_MMA(1, 1, At, B1); PG8_BAR; PG8_SCHED;
;             PG8_LDB(B0, 1, 0); PG8_LDB(B1, 1, 1); PG8_SCHED; PG8_LDA(At, 1, 0); PG8_STAGE(PG8_SA(0, 1), a2 + hstep, voffA);
;             PG8_WAIT_V(8); PG8_WAIT_L(0); PG8_BAR; PG8_MMA(0, 0, At, B0); PG8_MMA(0, 1, At, B1); PG8_BAR; PG8_SCHED;
	s_setprio 1
	s_waitcnt lgkmcnt(0)
	v_mfma_f32_16x16x32_bf16 v[62:65], v[142:145], v[174:177], v[62:65]
	v_mfma_f32_16x16x32_bf16 v[58:61], v[150:153], v[174:177], v[58:61]
	v_mfma_f32_16x16x32_bf16 v[46:49], v[142:145], v[182:185], v[46:49]
	v_mfma_f32_16x16x32_bf16 v[42:45], v[150:153], v[182:185], v[42:45]
	v_mfma_f32_16x16x32_bf16 v[30:33], v[142:145], v[190:193], v[30:33]
	v_mfma_f32_16x16x32_bf16 v[26:29], v[150:153], v[190:193], v[26:29]
	v_mfma_f32_16x16x32_bf16 v[14:17], v[142:145], v[198:201], v[14:17]
	v_mfma_f32_16x16x32_bf16 v[10:13], v[150:153], v[198:201], v[10:13]
	v_mfma_f32_16x16x32_bf16 v[62:65], v[146:149], v[178:181], v[62:65]
	v_mfma_f32_16x16x32_bf16 v[58:61], v[154:157], v[178:181], v[58:61]
	v_mfma_f32_16x16x32_bf16 v[46:49], v[146:149], v[186:189], v[46:49]
	v_mfma_f32_16x16x32_bf16 v[42:45], v[154:157], v[186:189], v[42:45]
	v_mfma_f32_16x16x32_bf16 v[30:33], v[146:149], v[194:197], v[30:33]
	v_mfma_f32_16x16x32_bf16 v[26:29], v[154:157], v[194:197], v[26:29]
	v_mfma_f32_16x16x32_bf16 v[14:17], v[146:149], v[202:205], v[14:17]
	v_mfma_f32_16x16x32_bf16 v[10:13], v[154:157], v[202:205], v[10:13]
	s_setprio 0
	s_setprio 1
	v_mfma_f32_16x16x32_bf16 v[54:57], v[158:161], v[174:177], v[54:57]
	v_mfma_f32_16x16x32_bf16 v[50:53], v[166:169], v[174:177], v[50:53]
	v_mfma_f32_16x16x32_bf16 v[38:41], v[158:161], v[182:185], v[38:41]
	v_mfma_f32_16x16x32_bf16 v[34:37], v[166:169], v[182:185], v[34:37]
	v_mfma_f32_16x16x32_bf16 v[22:25], v[158:161], v[190:193], v[22:25]
	v_mfma_f32_16x16x32_bf16 v[18:21], v[166:169], v[190:193], v[18:21]
	v_mfma_f32_16x16x32_bf16 v[6:9], v[158:161], v[198:201], v[6:9]
	v_mfma_f32_16x16x32_bf16 v[2:5], v[166:169], v[198:201], v[2:5]
	v_mfma_f32_16x16x32_bf16 v[54:57], v[162:165], v[178:181], v[54:57]
	v_mfma_f32_16x16x32_bf16 v[50:53], v[170:173], v[178:181], v[50:53]
	v_mfma_f32_16x16x32_bf16 v[38:41], v[162:165], v[186:189], v[38:41]
	v_mfma_f32_16x16x32_bf16 v[34:37], v[170:173], v[186:189], v[34:37]
	v_mfma_f32_16x16x32_bf16 v[22:25], v[162:165], v[194:197], v[22:25]
	v_mfma_f32_16x16x32_bf16 v[18:21], v[170:173], v[194:197], v[18:21]
	v_mfma_f32_16x16x32_bf16 v[6:9], v[162:165], v[202:205], v[6:9]
	v_mfma_f32_16x16x32_bf16 v[2:5], v[170:173], v[202:205], v[2:5]
	s_setprio 0
	s_barrier
	s_add_i32 s46, 0, 0x18000
	s_add_i32 s47, 0, 0x1c000
	v_add_u32_e32 v154, s46, v140
	v_add_u32_e32 v170, s47, v140
	ds_read_b128 v[142:145], v154
	ds_read_b128 v[146:149], v154 offset:1024
	ds_read_b128 v[150:153], v154 offset:2048
	ds_read_b128 v[154:157], v154 offset:3072
	ds_read_b128 v[158:161], v170
	ds_read_b128 v[162:165], v170 offset:1024
	ds_read_b128 v[166:169], v170 offset:2048
	ds_read_b128 v[170:173], v170 offset:3072
	s_add_u32 s28, s28, 0x40000
	s_addc_u32 s29, s29, 0
	v_mov_b32_e32 v206, v135
	s_mov_b32 m0, s35
	ds_read_b128 v[174:177], v141 offset:32768
	ds_read_b128 v[178:181], v141 offset:33792
	ds_read_b128 v[182:185], v141 offset:34816
	ds_read_b128 v[186:189], v141 offset:35840
	ds_read_b128 v[190:193], v141 offset:36864
	ds_read_b128 v[194:197], v141 offset:37888
	ds_read_b128 v[198:201], v141 offset:38912
	ds_read_b128 v[202:205], v141 offset:39936
	s_nop 0
	global_load_lds_dwordx4 v206, s[28:29]
	v_mov_b32_e32 v206, v137
	s_mov_b32 m0, s36
	s_nop 0
	global_load_lds_dwordx4 v206, s[28:29]
	s_waitcnt vmcnt(8)
	s_waitcnt lgkmcnt(0)
	s_barrier
	s_setprio 1
	s_waitcnt lgkmcnt(0)
	v_mfma_f32_16x16x32_bf16 v[126:129], v[142:145], v[174:177], v[126:129]
	v_mfma_f32_16x16x32_bf16 v[122:125], v[150:153], v[174:177], v[122:125]
	v_mfma_f32_16x16x32_bf16 v[110:113], v[142:145], v[182:185], v[110:113]
	v_mfma_f32_16x16x32_bf16 v[106:109], v[150:153], v[182:185], v[106:109]
	v_mfma_f32_16x16x32_bf16 v[94:97], v[142:145], v[190:193], v[94:97]
	v_mfma_f32_16x16x32_bf16 v[90:93], v[150:153], v[190:193], v[90:93]
	v_mfma_f32_16x16x32_bf16 v[78:81], v[142:145], v[198:201], v[78:81]
	v_mfma_f32_16x16x32_bf16 v[74:77], v[150:153], v[198:201], v[74:77]
	v_mfma_f32_16x16x32_bf16 v[126:129], v[146:149], v[178:181], v[126:129]
	v_mfma_f32_16x16x32_bf16 v[122:125], v[154:157], v[178:181], v[122:125]
	v_mfma_f32_16x16x32_bf16 v[110:113], v[146:149], v[186:189], v[110:113]
	v_mfma_f32_16x16x32_bf16 v[106:109], v[154:157], v[186:189], v[106:109]
	v_mfma_f32_16x16x32_bf16 v[94:97], v[146:149], v[194:197], v[94:97]
	v_mfma_f32_16x16x32_bf16 v[90:93], v[154:157], v[194:197], v[90:93]
	v_mfma_f32_16x16x32_bf16 v[78:81], v[146:149], v[202:205], v[78:81]
	v_mfma_f32_16x16x32_bf16 v[74:77], v[154:157], v[202:205], v[74:77]
	s_setprio 0
	s_setprio 1
	v_mfma_f32_16x16x32_bf16 v[118:121], v[158:161], v[174:177], v[118:121]
	v_mfma_f32_16x16x32_bf16 v[114:117], v[166:169], v[174:177], v[114:117]
	v_mfma_f32_16x16x32_bf16 v[102:105], v[158:161], v[182:185], v[102:105]
	v_mfma_f32_16x16x32_bf16 v[98:101], v[166:169], v[182:185], v[98:101]
	v_mfma_f32_16x16x32_bf16 v[86:89], v[158:161], v[190:193], v[86:89]
	v_mfma_f32_16x16x32_bf16 v[82:85], v[166:169], v[190:193], v[82:85]
	v_mfma_f32_16x16x32_bf16 v[70:73], v[158:161], v[198:201], v[70:73]
	v_mfma_f32_16x16x32_bf16 v[66:69], v[166:169], v[198:201], v[66:69]
	v_mfma_f32_16x16x32_bf16 v[118:121], v[162:165], v[178:181], v[118:121]
	v_mfma_f32_16x16x32_bf16 v[114:117], v[170:173], v[178:181], v[114:117]
	v_mfma_f32_16x16x32_bf16 v[102:105], v[162:165], v[186:189], v[102:105]
	v_mfma_f32_16x16x32_bf16 v[98:101], v[170:173], v[186:189], v[98:101]
	v_mfma_f32_16x16x32_bf16 v[86:89], v[162:165], v[194:197], v[86:89]
	v_mfma_f32_16x16x32_bf16 v[82:85], v[170:173], v[194:197], v[82:85]
	v_mfma_f32_16x16x32_bf16 v[70:73], v[162:165], v[202:205], v[70:73]
	v_mfma_f32_16x16x32_bf16 v[66:69], v[170:173], v[202:205], v[66:69]
	s_setprio 0
	s_barrier
;     ...
;             PG8_LDA(At, 1, 1); PG8_STAGE(PG8_SB(1, 0), b3, voffB); PG8_STAGE(PG8_SB(1, 1), b3 + hstepB, voffB); PG8_STAGE(PG8_SA(1, 0), a3, voffA);
;             PG8_WAIT_V(8); PG8_WAIT_L(0); PG8_BAR; PG8_MMA(1, 0, At, B0); PG8_MMA(1, 1, At, B1); PG8_BAR; PG8_SCHED;
;             } else {
;             PG8_LDB(B0, 0, 0); PG8_SCHED; PG8_LDA(At, 0, 0); PG8_STAGE(PG8_SA(1, 1), a1 + hstep, voffA);
;             PG8_WAIT_L(8); PG8_BAR; PG8_WAIT_L(0); PG8_MMA(0, 0, At, B0); PG8_BAR; PG8_SCHED;
;             PG8_LDB(B1, 0, 1); PG8_STAGE(PG8_SB(0, 0), b2, voffB);
;             PG8_BAR; PG8_WAIT_L(0); PG8_MMA(0, 1, At, B1); PG8_BAR;
;             PG8_LDA(At, 0, 1); PG8_STAGE(PG8_SA(0, 0), a2, voffA);
;             PG8_BAR; PG8_WAIT_L(0); PG8_MMA(1, 0, At, B0); PG8_BAR; PG8_SCHED;
;             PG8_STAGE(PG8_SB(0, 1), b2 + hstepB, voffB);
;             PG8_WAIT_V(6); PG8_BAR; PG8_MMA(1, 1, At, B1); PG8_BAR;
;             PG8_LDB(B0, 1, 0); PG8_SCHED; PG8_LDA(At, 1, 0); PG8_STAGE(PG8_SA(0, 1), a2 + hstep, voffA);
;             PG8_WAIT_L(8); PG8_BAR; PG8_WAIT_L(0); PG8_MMA(0, 0, At, B0); PG8_BAR; PG8_SCHED;
;             PG8_LDB(B1, 1, 1); PG8_STAGE(PG8_SB(1, 0), b3, voffB);
;             PG8_BAR; PG8_WAIT_L(0); PG8_MMA(0, 1, At, B1); PG8_BAR;
;             PG8_LDA(At, 1, 1); PG8_STAGE(PG8_SA(1, 0), a3, voffA);
;             PG8_BAR; PG8_WAIT_L(0); PG8_MMA(1, 0, At, B0); PG8_BAR; PG8_SCHED;
;             PG8_STAGE(PG8_SB(1, 1), b3 + hstepB, voffB);
;             PG8_WAIT_V(6); PG8_BAR; PG8_MMA(1, 1, At, B1); PG8_BAR;
;             }
;         }
;         if constexpr (ALIGN_EPI) { if (wr == 0) PG8_BAR; }
;         if (GP) { gpEnd = __builtin_amdgcn_s_memrealtime(); if (ui == 0) accFirst0 += gp1 - gpU; else accFirst += gp1 - gpU; accSteady += gpEnd - gp1; }
;         if constexpr (!Epi::AFTER_DRAIN) { E(acc, cur, wr, wc, fr, fq); S.done(cur); }
;         if (GP) accE += __builtin_amdgcn_s_memrealtime() - gpEnd;
;         if (!has_next) break;
;         if constexpr (!Epi::KEEP_ACC) {
; #pragma unroll
;         for (int a = 0; a < 2; ++a)
; #pragma unroll
;             for (int b = 0; b < 2; ++b)
; #pragma unroll
;                 for (int m = 0; m < 4; ++m)
; #pragma unroll
;                     for (int n = 0; n < 2; ++n) acc[a][b][m][n] = (f32x4){0.f, 0.f, 0.f, 0.f};
;         }
;         cur = nxt; cA = nA; cB = nB; ++ui;
	s_add_u32 s28, s26, 0x80
	s_addc_u32 s29, s27, 0
	v_mov_b32_e32 v206, v136
	s_add_i32 s46, s46, s1
	ds_read_b128 v[174:177], v141 offset:49152
	ds_read_b128 v[178:181], v141 offset:50176
	ds_read_b128 v[182:185], v141 offset:51200
	ds_read_b128 v[186:189], v141 offset:52224
	ds_read_b128 v[190:193], v141 offset:53248
	ds_read_b128 v[194:197], v141 offset:54272
	ds_read_b128 v[198:201], v141 offset:55296
	ds_read_b128 v[202:205], v141 offset:56320
	s_mov_b32 m0, s46
	s_nop 0
	global_load_lds_dwordx4 v206, s[28:29]
	v_mov_b32_e32 v206, v138
	s_add_i32 m0, s46, 0x2000
	s_add_u32 s26, s26, 0x40080
	global_load_lds_dwordx4 v206, s[28:29]
	s_addc_u32 s27, s27, 0
	v_mov_b32_e32 v206, v136
	s_add_i32 s28, s47, s1
	s_mov_b32 m0, s28
	s_nop 0
	global_load_lds_dwordx4 v206, s[26:27]
	v_mov_b32_e32 v206, v138
	s_add_i32 m0, s28, 0x2000
	s_nop 0
	global_load_lds_dwordx4 v206, s[26:27]
	v_mov_b32_e32 v206, v135
	s_mov_b32 m0, s38
	s_nop 0
	global_load_lds_dwordx4 v206, s[24:25]
	v_mov_b32_e32 v206, v137
	s_mov_b32 m0, s39
	s_nop 0
	global_load_lds_dwordx4 v206, s[24:25]
	s_waitcnt vmcnt(8)
	s_waitcnt lgkmcnt(0)
	s_barrier
	s_setprio 1
	s_waitcnt lgkmcnt(0)
	v_mfma_f32_16x16x32_bf16 v[62:65], v[142:145], v[174:177], v[62:65]
	v_mfma_f32_16x16x32_bf16 v[58:61], v[150:153], v[174:177], v[58:61]
	v_mfma_f32_16x16x32_bf16 v[46:49], v[142:145], v[182:185], v[46:49]
	v_mfma_f32_16x16x32_bf16 v[42:45], v[150:153], v[182:185], v[42:45]
	v_mfma_f32_16x16x32_bf16 v[30:33], v[142:145], v[190:193], v[30:33]
	v_mfma_f32_16x16x32_bf16 v[26:29], v[150:153], v[190:193], v[26:29]
	v_mfma_f32_16x16x32_bf16 v[14:17], v[142:145], v[198:201], v[14:17]
	v_mfma_f32_16x16x32_bf16 v[10:13], v[150:153], v[198:201], v[10:13]
	v_mfma_f32_16x16x32_bf16 v[62:65], v[146:149], v[178:181], v[62:65]
	v_mfma_f32_16x16x32_bf16 v[58:61], v[154:157], v[178:181], v[58:61]
	v_mfma_f32_16x16x32_bf16 v[46:49], v[146:149], v[186:189], v[46:49]
	v_mfma_f32_16x16x32_bf16 v[42:45], v[154:157], v[186:189], v[42:45]
	v_mfma_f32_16x16x32_bf16 v[30:33], v[146:149], v[194:197], v[30:33]
	v_mfma_f32_16x16x32_bf16 v[26:29], v[154:157], v[194:197], v[26:29]
	v_mfma_f32_16x16x32_bf16 v[14:17], v[146:149], v[202:205], v[14:17]
	v_mfma_f32_16x16x32_bf16 v[10:13], v[154:157], v[202:205], v[10:13]
	s_setprio 0
	s_setprio 1
	v_mfma_f32_16x16x32_bf16 v[54:57], v[158:161], v[174:177], v[54:57]
	v_mfma_f32_16x16x32_bf16 v[50:53], v[166:169], v[174:177], v[50:53]
	v_mfma_f32_16x16x32_bf16 v[38:41], v[158:161], v[182:185], v[38:41]
	v_mfma_f32_16x16x32_bf16 v[34:37], v[166:169], v[182:185], v[34:37]
	v_mfma_f32_16x16x32_bf16 v[22:25], v[158:161], v[190:193], v[22:25]
	v_mfma_f32_16x16x32_bf16 v[18:21], v[166:169], v[190:193], v[18:21]
	v_mfma_f32_16x16x32_bf16 v[6:9], v[158:161], v[198:201], v[6:9]
	v_mfma_f32_16x16x32_bf16 v[2:5], v[166:169], v[198:201], v[2:5]
	v_mfma_f32_16x16x32_bf16 v[54:57], v[162:165], v[178:181], v[54:57]
	v_mfma_f32_16x16x32_bf16 v[50:53], v[170:173], v[178:181], v[50:53]
	v_mfma_f32_16x16x32_bf16 v[38:41], v[162:165], v[186:189], v[38:41]
	v_mfma_f32_16x16x32_bf16 v[34:37], v[170:173], v[186:189], v[34:37]
	v_mfma_f32_16x16x32_bf16 v[22:25], v[162:165], v[194:197], v[22:25]
	v_mfma_f32_16x16x32_bf16 v[18:21], v[170:173], v[194:197], v[18:21]
	v_mfma_f32_16x16x32_bf16 v[6:9], v[162:165], v[202:205], v[6:9]
	v_mfma_f32_16x16x32_bf16 v[2:5], v[170:173], v[202:205], v[2:5]
	s_setprio 0
	s_barrier
	s_add_i32 s45, s45, 2
	s_add_u32 s22, s22, 0x100
	s_addc_u32 s23, s23, 0
	s_cmp_gt_u32 s45, 13
	s_cbranch_scc0 .LBB0_799
	s_andn2_b64 vcc, exec, s[4:5]
	s_cbranch_vccnz .LBB0_791
	v_mov_b32_e32 v2, 0
	s_mov_b32 s0, s16
	s_mov_b32 s10, s18
	s_mov_b64 s[12:13], s[20:21]
	s_mov_b64 s[14:15], s[2:3]
	s_mov_b32 s37, s42
	v_mov_b32_e32 v3, v2
	v_mov_b32_e32 v4, v2
	v_mov_b32_e32 v5, v2
	v_mov_b32_e32 v6, v2
	v_mov_b32_e32 v7, v2
	v_mov_b32_e32 v8, v2
	v_mov_b32_e32 v9, v2
	v_mov_b32_e32 v18, v2
	v_mov_b32_e32 v19, v2
	v_mov_b32_e32 v20, v2
	v_mov_b32_e32 v21, v2
	v_mov_b32_e32 v22, v2
	v_mov_b32_e32 v23, v2
	v_mov_b32_e32 v24, v2
	v_mov_b32_e32 v25, v2
	v_mov_b32_e32 v34, v2
	v_mov_b32_e32 v35, v2
	v_mov_b32_e32 v36, v2
	v_mov_b32_e32 v37, v2
	v_mov_b32_e32 v38, v2
	v_mov_b32_e32 v39, v2
	v_mov_b32_e32 v40, v2
	v_mov_b32_e32 v41, v2
	v_mov_b32_e32 v50, v2
	v_mov_b32_e32 v51, v2
	v_mov_b32_e32 v52, v2
	v_mov_b32_e32 v53, v2
	v_mov_b32_e32 v54, v2
	v_mov_b32_e32 v55, v2
	v_mov_b32_e32 v56, v2
	v_mov_b32_e32 v57, v2
	v_mov_b32_e32 v10, v2
	v_mov_b32_e32 v11, v2
	v_mov_b32_e32 v12, v2
	v_mov_b32_e32 v13, v2
	v_mov_b32_e32 v14, v2
	v_mov_b32_e32 v15, v2
	v_mov_b32_e32 v16, v2
	v_mov_b32_e32 v17, v2
	v_mov_b32_e32 v26, v2
	v_mov_b32_e32 v27, v2
	v_mov_b32_e32 v28, v2
	v_mov_b32_e32 v29, v2
	v_mov_b32_e32 v30, v2
	v_mov_b32_e32 v31, v2
	v_mov_b32_e32 v32, v2
	v_mov_b32_e32 v33, v2
	v_mov_b32_e32 v42, v2
	v_mov_b32_e32 v43, v2
	v_mov_b32_e32 v44, v2
	v_mov_b32_e32 v45, v2
	v_mov_b32_e32 v46, v2
	v_mov_b32_e32 v47, v2
	v_mov_b32_e32 v48, v2
	v_mov_b32_e32 v49, v2
	v_mov_b32_e32 v58, v2
	v_mov_b32_e32 v59, v2
	v_mov_b32_e32 v60, v2
	v_mov_b32_e32 v61, v2
	v_mov_b32_e32 v62, v2
	v_mov_b32_e32 v63, v2
	v_mov_b32_e32 v64, v2
	v_mov_b32_e32 v65, v2
	v_mov_b32_e32 v66, v2
	v_mov_b32_e32 v67, v2
	v_mov_b32_e32 v68, v2
	v_mov_b32_e32 v69, v2
	v_mov_b32_e32 v70, v2
	v_mov_b32_e32 v71, v2
	v_mov_b32_e32 v72, v2
	v_mov_b32_e32 v73, v2
	v_mov_b32_e32 v82, v2
	v_mov_b32_e32 v83, v2
	v_mov_b32_e32 v84, v2
	v_mov_b32_e32 v85, v2
	v_mov_b32_e32 v86, v2
	v_mov_b32_e32 v87, v2
	v_mov_b32_e32 v88, v2
	v_mov_b32_e32 v89, v2
	v_mov_b32_e32 v98, v2
	v_mov_b32_e32 v99, v2
	v_mov_b32_e32 v100, v2
	v_mov_b32_e32 v101, v2
	v_mov_b32_e32 v102, v2
	v_mov_b32_e32 v103, v2
	v_mov_b32_e32 v104, v2
	v_mov_b32_e32 v105, v2
	v_mov_b32_e32 v114, v2
	v_mov_b32_e32 v115, v2
	v_mov_b32_e32 v116, v2
	v_mov_b32_e32 v117, v2
	v_mov_b32_e32 v118, v2
	v_mov_b32_e32 v119, v2
	v_mov_b32_e32 v120, v2
	v_mov_b32_e32 v121, v2
	v_mov_b32_e32 v74, v2
	v_mov_b32_e32 v75, v2
	v_mov_b32_e32 v76, v2
	v_mov_b32_e32 v77, v2
	v_mov_b32_e32 v78, v2
	v_mov_b32_e32 v79, v2
	v_mov_b32_e32 v80, v2
	v_mov_b32_e32 v81, v2
	v_mov_b32_e32 v90, v2
	v_mov_b32_e32 v91, v2
	v_mov_b32_e32 v92, v2
	v_mov_b32_e32 v93, v2
	v_mov_b32_e32 v94, v2
	v_mov_b32_e32 v95, v2
	v_mov_b32_e32 v96, v2
	v_mov_b32_e32 v97, v2
	v_mov_b32_e32 v106, v2
	v_mov_b32_e32 v107, v2
	v_mov_b32_e32 v108, v2
	v_mov_b32_e32 v109, v2
	v_mov_b32_e32 v110, v2
	v_mov_b32_e32 v111, v2
	v_mov_b32_e32 v112, v2
	v_mov_b32_e32 v113, v2
	v_mov_b32_e32 v122, v2
	v_mov_b32_e32 v123, v2
	v_mov_b32_e32 v124, v2
	v_mov_b32_e32 v125, v2
	v_mov_b32_e32 v126, v2
	v_mov_b32_e32 v127, v2
	v_mov_b32_e32 v128, v2
	v_mov_b32_e32 v129, v2
	s_branch .LBB0_791

; #define PG8_STAGE(bufoff, gbase, voff) do { const char* gb_ = (const char*)(gbase); asm volatile("" : "+s"(gb_)); _Pragma("unroll") for (int _i = 0; _i < 2; ++_i) { unsigned vo_ = (voff)[_i]; asm volatile("" : "+v"(vo_)); \
;         __builtin_amdgcn_global_load_lds((const unsigned*)(gb_ + vo_), (PG8_LAS unsigned*)(lds + (bufoff) + ldsw + _i * 8192), 16, 0, 0); } } while (0)
; #define PG8_LDA(dst, b, h) do { _Pragma("unroll") for (int m = 0; m < 4; ++m) _Pragma("unroll") for (int k = 0; k < 2; ++k) dst[m][k] = *(const PG8_LAS bf16x8*)(lds + PG8_SA(b, h) + aoff + m * 2048 + k * 1024); } while (0)
; #define PG8_LDB(dst, b, h) do { _Pragma("unroll") for (int n = 0; n < 2; ++n) _Pragma("unroll") for (int k = 0; k < 2; ++k) dst[n][k] = *(const PG8_LAS bf16x8*)(lds + PG8_SB(b, h) + boff + n * 2048 + k * 1024); } while (0)
; #define PG8_MMA(ai, bj, At, Bt) do { __builtin_amdgcn_s_setprio(1); _Pragma("unroll") for (int m = 0; m < 4; ++m) _Pragma("unroll") for (int n = 0; n < 2; ++n) _Pragma("unroll") for (int k = 0; k < 2; ++k) \
;         acc[ai][bj][m][n] = __builtin_amdgcn_mfma_f32_16x16x32_bf16(Bt[n][k], At[m][k], acc[ai][bj][m][n], 0, 0, 0); __builtin_amdgcn_s_setprio(0); } while (0)
; #define PG8_WAIT_V(n) asm volatile("s_waitcnt vmcnt(" #n ")" ::: "memory")
; #define PG8_WAIT_L(n) asm volatile("s_waitcnt lgkmcnt(" #n ")" ::: "memory")
; #define PG8_BAR __builtin_amdgcn_s_barrier()
; #define PG8_SCHED __builtin_amdgcn_sched_barrier(0)
;     ...
;         for (int t = 0; t < nt; t += 2) {
;             const bool last = (t == nt - 2);
;             if (GP && t == 2) gp1 = __builtin_amdgcn_s_memrealtime();
;             const char* a1 = cA + (size_t)(t + 1) * kstep;
;             const char* a2 = last ? nA : cA + (size_t)(t + 2) * kstep; const char* b2 = last ? nB : cB + (size_t)(t + 2) * kstep;
;             const char* a3 = a2 + kstep; const char* b3 = b2 + kstep;
;             if (last && has_next) S.a_ready(nxt);
;             if constexpr (SP2) {
;             PG8_LDB(B0, 0, 0); PG8_LDB(B1, 0, 1); PG8_SCHED; PG8_LDA(At, 0, 0); PG8_STAGE(PG8_SA(1, 1), a1 + hstep, voffA);
;             PG8_WAIT_V(8); PG8_WAIT_L(0); PG8_BAR; PG8_MMA(0, 0, At, B0); PG8_MMA(0, 1, At, B1); PG8_BAR; PG8_SCHED;
;             PG8_LDA(At, 0, 1); PG8_STAGE(PG8_SB(0, 0), b2, voffB); PG8_STAGE(PG8_SB(0, 1), b2 + hstepB, voffB); PG8_STAGE(PG8_SA(0, 0), a2, voffA);
.LBB0_895:
	ds_read_b128 v[146:149], v142
	ds_read_b128 v[150:153], v142 offset:1024
	ds_read_b128 v[154:157], v142 offset:2048
	ds_read_b128 v[158:161], v142 offset:3072
	ds_read_b128 v[162:165], v143
	ds_read_b128 v[166:169], v143 offset:1024
	ds_read_b128 v[170:173], v143 offset:2048
	s_waitcnt lgkmcnt(6)
	ds_read_b128 v[174:177], v143 offset:3072
	s_add_u32 s20, s18, 0x100
	s_addc_u32 s21, s19, 0
	s_cmp_eq_u32 s54, 12
	s_cselect_b32 s26, s50, s20
	s_cselect_b32 s27, s11, s21
	s_cselect_b32 s24, s51, s52
	s_cselect_b32 s25, s7, s53
	s_add_u32 s22, s26, 0x80
	s_addc_u32 s23, s27, 0
	s_add_u32 s18, s18, 0x40080
	s_addc_u32 s19, s19, 0
	v_mov_b32_e32 v136, v1
	ds_read_b128 v[178:181], v144
	ds_read_b128 v[182:185], v144 offset:1024
	ds_read_b128 v[186:189], v144 offset:2048
	ds_read_b128 v[190:193], v144 offset:3072
	ds_read_b128 v[194:197], v144 offset:4096
	ds_read_b128 v[198:201], v144 offset:5120
	ds_read_b128 v[202:205], v144 offset:6144
	ds_read_b128 v[206:209], v144 offset:7168
	s_add_i32 m0, s17, 0xc000
	s_nop 0
	global_load_lds_dwordx4 v136, s[18:19]
	v_mov_b32_e32 v136, v139
	s_add_i32 m0, s17, 0xe000
	s_nop 0
	global_load_lds_dwordx4 v136, s[18:19]
	s_waitcnt vmcnt(8)
	s_waitcnt lgkmcnt(0)
	s_barrier
	s_setprio 1
	s_waitcnt lgkmcnt(0)
	v_mfma_f32_16x16x32_bf16 v[126:129], v[146:149], v[178:181], v[126:129]
	v_mfma_f32_16x16x32_bf16 v[122:125], v[154:157], v[178:181], v[122:125]
	v_mfma_f32_16x16x32_bf16 v[114:117], v[146:149], v[186:189], v[114:117]
	v_mfma_f32_16x16x32_bf16 v[106:109], v[154:157], v[186:189], v[106:109]
	v_mfma_f32_16x16x32_bf16 v[98:101], v[146:149], v[194:197], v[98:101]
	v_mfma_f32_16x16x32_bf16 v[90:93], v[154:157], v[194:197], v[90:93]
	v_mfma_f32_16x16x32_bf16 v[82:85], v[146:149], v[202:205], v[82:85]
	v_mfma_f32_16x16x32_bf16 v[74:77], v[154:157], v[202:205], v[74:77]
	v_mfma_f32_16x16x32_bf16 v[126:129], v[150:153], v[182:185], v[126:129]
	v_mfma_f32_16x16x32_bf16 v[122:125], v[158:161], v[182:185], v[122:125]
	v_mfma_f32_16x16x32_bf16 v[114:117], v[150:153], v[190:193], v[114:117]
	v_mfma_f32_16x16x32_bf16 v[106:109], v[158:161], v[190:193], v[106:109]
	v_mfma_f32_16x16x32_bf16 v[98:101], v[150:153], v[198:201], v[98:101]
	v_mfma_f32_16x16x32_bf16 v[90:93], v[158:161], v[198:201], v[90:93]
	v_mfma_f32_16x16x32_bf16 v[82:85], v[150:153], v[206:209], v[82:85]
	v_mfma_f32_16x16x32_bf16 v[74:77], v[158:161], v[206:209], v[74:77]
	s_setprio 0
	s_setprio 1
	v_mfma_f32_16x16x32_bf16 v[118:121], v[162:165], v[178:181], v[118:121]
	v_mfma_f32_16x16x32_bf16 v[110:113], v[170:173], v[178:181], v[110:113]
	v_mfma_f32_16x16x32_bf16 v[102:105], v[162:165], v[186:189], v[102:105]
	v_mfma_f32_16x16x32_bf16 v[94:97], v[170:173], v[186:189], v[94:97]
	v_mfma_f32_16x16x32_bf16 v[86:89], v[162:165], v[194:197], v[86:89]
	v_mfma_f32_16x16x32_bf16 v[78:81], v[170:173], v[194:197], v[78:81]
	v_mfma_f32_16x16x32_bf16 v[70:73], v[162:165], v[202:205], v[70:73]
	v_mfma_f32_16x16x32_bf16 v[66:69], v[170:173], v[202:205], v[66:69]
	v_mfma_f32_16x16x32_bf16 v[118:121], v[166:169], v[182:185], v[118:121]
	v_mfma_f32_16x16x32_bf16 v[110:113], v[174:177], v[182:185], v[110:113]
	v_mfma_f32_16x16x32_bf16 v[102:105], v[166:169], v[190:193], v[102:105]
	v_mfma_f32_16x16x32_bf16 v[94:97], v[174:177], v[190:193], v[94:97]
	v_mfma_f32_16x16x32_bf16 v[86:89], v[166:169], v[198:201], v[86:89]
	v_mfma_f32_16x16x32_bf16 v[78:81], v[174:177], v[198:201], v[78:81]
	v_mfma_f32_16x16x32_bf16 v[70:73], v[166:169], v[206:209], v[70:73]
	v_mfma_f32_16x16x32_bf16 v[66:69], v[174:177], v[206:209], v[66:69]
	s_setprio 0
	s_barrier
	s_mov_b64 s[18:19], s[24:25]
	v_mov_b32_e32 v136, v138
	s_add_i32 s55, s39, s29
	ds_read_b128 v[178:181], v144 offset:16384
	ds_read_b128 v[182:185], v144 offset:17408
	ds_read_b128 v[186:189], v144 offset:18432
	ds_read_b128 v[190:193], v144 offset:19456
	ds_read_b128 v[194:197], v144 offset:20480
	ds_read_b128 v[198:201], v144 offset:21504
	ds_read_b128 v[202:205], v144 offset:22528
	ds_read_b128 v[206:209], v144 offset:23552
	s_mov_b32 m0, s55
	s_nop 0
	global_load_lds_dwordx4 v136, s[18:19]
	v_mov_b32_e32 v136, v140
	s_add_i32 m0, s55, 0x2000
	s_nop 0
	global_load_lds_dwordx4 v136, s[18:19]
	s_add_u32 s18, s24, 0x10000
	s_addc_u32 s19, s25, 0
	v_mov_b32_e32 v136, v138
	s_add_i32 s55, s40, s29
	s_mov_b32 m0, s55
	s_nop 0
	global_load_lds_dwordx4 v136, s[18:19]
	v_mov_b32_e32 v136, v140
	s_add_i32 m0, s55, 0x2000
	s_nop 0
	global_load_lds_dwordx4 v136, s[18:19]
	s_mov_b64 s[18:19], s[26:27]
	v_mov_b32_e32 v136, v1
	s_mov_b32 m0, s17
	s_nop 0
	global_load_lds_dwordx4 v136, s[18:19]
	v_mov_b32_e32 v136, v139
	s_mov_b32 m0, s30
	s_nop 0
	global_load_lds_dwordx4 v136, s[18:19]
	s_waitcnt vmcnt(8)
	s_waitcnt lgkmcnt(0)
	s_barrier
; #define PG8_STAGE(bufoff, gbase, voff) do { const char* gb_ = (const char*)(gbase); asm volatile("" : "+s"(gb_)); _Pragma("unroll") for (int _i = 0; _i < 2; ++_i) { unsigned vo_ = (voff)[_i]; asm volatile("" : "+v"(vo_)); \
;         __builtin_amdgcn_global_load_lds((const unsigned*)(gb_ + vo_), (PG8_LAS unsigned*)(lds + (bufoff) + ldsw + _i * 8192), 16, 0, 0); } } while (0)
; #define PG8_LDA(dst, b, h) do { _Pragma("unroll") for (int m = 0; m < 4; ++m) _Pragma("unroll") for (int k = 0; k < 2; ++k) dst[m][k] = *(const PG8_LAS bf16x8*)(lds + PG8_SA(b, h) + aoff + m * 2048 + k * 1024); } while (0)
; #define PG8_LDB(dst, b, h) do { _Pragma("unroll") for (int n = 0; n < 2; ++n) _Pragma("unroll") for (int k = 0; k < 2; ++k) dst[n][k] = *(const PG8_LAS bf16x8*)(lds + PG8_SB(b, h) + boff + n * 2048 + k * 1024); } while (0)
; #define PG8_MMA(ai, bj, At, Bt) do { __builtin_amdgcn_s_setprio(1); _Pragma("unroll") for (int m = 0; m < 4; ++m) _Pragma("unroll") for (int n = 0; n < 2; ++n) _Pragma("unroll") for (int k = 0; k < 2; ++k) \
;         acc[ai][bj][m][n] = __builtin_amdgcn_mfma_f32_16x16x32_bf16(Bt[n][k], At[m][k], acc[ai][bj][m][n], 0, 0, 0); __builtin_amdgcn_s_setprio(0); } while (0)
; #define PG8_WAIT_V(n) asm volatile("s_waitcnt vmcnt(" #n ")" ::: "memory")
; #define PG8_WAIT_L(n) asm volatile("s_waitcnt lgkmcnt(" #n ")" ::: "memory")
; #define PG8_BAR __builtin_amdgcn_s_barrier()
; #define PG8_SCHED __builtin_amdgcn_sched_barrier(0)
;     ...
;             PG8_WAIT_V(8); PG8_WAIT_L(0); PG8_BAR; PG8_MMA(1, 0, At, B0); PG8_MMA(1, 1, At, B1); PG8_BAR; PG8_SCHED;
;             PG8_LDB(B0, 1, 0); PG8_LDB(B1, 1, 1); PG8_SCHED; PG8_LDA(At, 1, 0); PG8_STAGE(PG8_SA(0, 1), a2 + hstep, voffA);
;             PG8_WAIT_V(8); PG8_WAIT_L(0); PG8_BAR; PG8_MMA(0, 0, At, B0); PG8_MMA(0, 1, At, B1); PG8_BAR; PG8_SCHED;
	s_setprio 1
	s_waitcnt lgkmcnt(0)
	v_mfma_f32_16x16x32_bf16 v[62:65], v[146:149], v[178:181], v[62:65]
	v_mfma_f32_16x16x32_bf16 v[58:61], v[154:157], v[178:181], v[58:61]
	v_mfma_f32_16x16x32_bf16 v[50:53], v[146:149], v[186:189], v[50:53]
	v_mfma_f32_16x16x32_bf16 v[42:45], v[154:157], v[186:189], v[42:45]
	v_mfma_f32_16x16x32_bf16 v[34:37], v[146:149], v[194:197], v[34:37]
	v_mfma_f32_16x16x32_bf16 v[26:29], v[154:157], v[194:197], v[26:29]
	v_mfma_f32_16x16x32_bf16 v[18:21], v[146:149], v[202:205], v[18:21]
	v_mfma_f32_16x16x32_bf16 v[10:13], v[154:157], v[202:205], v[10:13]
	v_mfma_f32_16x16x32_bf16 v[62:65], v[150:153], v[182:185], v[62:65]
	v_mfma_f32_16x16x32_bf16 v[58:61], v[158:161], v[182:185], v[58:61]
	v_mfma_f32_16x16x32_bf16 v[50:53], v[150:153], v[190:193], v[50:53]
	v_mfma_f32_16x16x32_bf16 v[42:45], v[158:161], v[190:193], v[42:45]
	v_mfma_f32_16x16x32_bf16 v[34:37], v[150:153], v[198:201], v[34:37]
	v_mfma_f32_16x16x32_bf16 v[26:29], v[158:161], v[198:201], v[26:29]
	v_mfma_f32_16x16x32_bf16 v[18:21], v[150:153], v[206:209], v[18:21]
	v_mfma_f32_16x16x32_bf16 v[10:13], v[158:161], v[206:209], v[10:13]
	s_setprio 0
	s_setprio 1
	v_mfma_f32_16x16x32_bf16 v[54:57], v[162:165], v[178:181], v[54:57]
	v_mfma_f32_16x16x32_bf16 v[46:49], v[170:173], v[178:181], v[46:49]
	v_mfma_f32_16x16x32_bf16 v[38:41], v[162:165], v[186:189], v[38:41]
	v_mfma_f32_16x16x32_bf16 v[30:33], v[170:173], v[186:189], v[30:33]
	v_mfma_f32_16x16x32_bf16 v[22:25], v[162:165], v[194:197], v[22:25]
	v_mfma_f32_16x16x32_bf16 v[14:17], v[170:173], v[194:197], v[14:17]
	v_mfma_f32_16x16x32_bf16 v[6:9], v[162:165], v[202:205], v[6:9]
	v_mfma_f32_16x16x32_bf16 v[2:5], v[170:173], v[202:205], v[2:5]
	v_mfma_f32_16x16x32_bf16 v[54:57], v[166:169], v[182:185], v[54:57]
	v_mfma_f32_16x16x32_bf16 v[46:49], v[174:177], v[182:185], v[46:49]
	v_mfma_f32_16x16x32_bf16 v[38:41], v[166:169], v[190:193], v[38:41]
	v_mfma_f32_16x16x32_bf16 v[30:33], v[174:177], v[190:193], v[30:33]
	v_mfma_f32_16x16x32_bf16 v[22:25], v[166:169], v[198:201], v[22:25]
	v_mfma_f32_16x16x32_bf16 v[14:17], v[174:177], v[198:201], v[14:17]
	v_mfma_f32_16x16x32_bf16 v[6:9], v[166:169], v[206:209], v[6:9]
	v_mfma_f32_16x16x32_bf16 v[2:5], v[174:177], v[206:209], v[2:5]
	s_setprio 0
	s_barrier
	s_add_i32 s55, 0, 0x18000
	v_add_u32_e32 v136, s55, v141
	s_add_i32 s56, 0, 0x1c000
	ds_read_b128 v[146:149], v136
	ds_read_b128 v[150:153], v136 offset:1024
	ds_read_b128 v[154:157], v136 offset:2048
	ds_read_b128 v[158:161], v136 offset:3072
	v_add_u32_e32 v136, s56, v141
	ds_read_b128 v[162:165], v136
	ds_read_b128 v[166:169], v136 offset:1024
	ds_read_b128 v[170:173], v136 offset:2048
	ds_read_b128 v[174:177], v136 offset:3072
	s_add_u32 s18, s26, 0x40000
	s_addc_u32 s19, s27, 0
	v_mov_b32_e32 v136, v1
	s_mov_b32 m0, s31
	ds_read_b128 v[178:181], v144 offset:32768
	ds_read_b128 v[182:185], v144 offset:33792
	ds_read_b128 v[186:189], v144 offset:34816
	ds_read_b128 v[190:193], v144 offset:35840
	ds_read_b128 v[194:197], v144 offset:36864
	ds_read_b128 v[198:201], v144 offset:37888
	ds_read_b128 v[202:205], v144 offset:38912
	ds_read_b128 v[206:209], v144 offset:39936
	s_nop 0
	global_load_lds_dwordx4 v136, s[18:19]
	v_mov_b32_e32 v136, v139
	s_mov_b32 m0, s33
	s_nop 0
	global_load_lds_dwordx4 v136, s[18:19]
	s_waitcnt vmcnt(8)
	s_waitcnt lgkmcnt(0)
	s_barrier
	s_setprio 1
	s_waitcnt lgkmcnt(0)
	v_mfma_f32_16x16x32_bf16 v[126:129], v[146:149], v[178:181], v[126:129]
	v_mfma_f32_16x16x32_bf16 v[122:125], v[154:157], v[178:181], v[122:125]
	v_mfma_f32_16x16x32_bf16 v[114:117], v[146:149], v[186:189], v[114:117]
	v_mfma_f32_16x16x32_bf16 v[106:109], v[154:157], v[186:189], v[106:109]
	v_mfma_f32_16x16x32_bf16 v[98:101], v[146:149], v[194:197], v[98:101]
	v_mfma_f32_16x16x32_bf16 v[90:93], v[154:157], v[194:197], v[90:93]
	v_mfma_f32_16x16x32_bf16 v[82:85], v[146:149], v[202:205], v[82:85]
	v_mfma_f32_16x16x32_bf16 v[74:77], v[154:157], v[202:205], v[74:77]
	v_mfma_f32_16x16x32_bf16 v[126:129], v[150:153], v[182:185], v[126:129]
	v_mfma_f32_16x16x32_bf16 v[122:125], v[158:161], v[182:185], v[122:125]
	v_mfma_f32_16x16x32_bf16 v[114:117], v[150:153], v[190:193], v[114:117]
	v_mfma_f32_16x16x32_bf16 v[106:109], v[158:161], v[190:193], v[106:109]
	v_mfma_f32_16x16x32_bf16 v[98:101], v[150:153], v[198:201], v[98:101]
	v_mfma_f32_16x16x32_bf16 v[90:93], v[158:161], v[198:201], v[90:93]
	v_mfma_f32_16x16x32_bf16 v[82:85], v[150:153], v[206:209], v[82:85]
	v_mfma_f32_16x16x32_bf16 v[74:77], v[158:161], v[206:209], v[74:77]
	s_setprio 0
	s_setprio 1
	v_mfma_f32_16x16x32_bf16 v[118:121], v[162:165], v[178:181], v[118:121]
	v_mfma_f32_16x16x32_bf16 v[110:113], v[170:173], v[178:181], v[110:113]
	v_mfma_f32_16x16x32_bf16 v[102:105], v[162:165], v[186:189], v[102:105]
	v_mfma_f32_16x16x32_bf16 v[94:97], v[170:173], v[186:189], v[94:97]
	v_mfma_f32_16x16x32_bf16 v[86:89], v[162:165], v[194:197], v[86:89]
	v_mfma_f32_16x16x32_bf16 v[78:81], v[170:173], v[194:197], v[78:81]
	v_mfma_f32_16x16x32_bf16 v[70:73], v[162:165], v[202:205], v[70:73]
	v_mfma_f32_16x16x32_bf16 v[66:69], v[170:173], v[202:205], v[66:69]
	v_mfma_f32_16x16x32_bf16 v[118:121], v[166:169], v[182:185], v[118:121]
	v_mfma_f32_16x16x32_bf16 v[110:113], v[174:177], v[182:185], v[110:113]
	v_mfma_f32_16x16x32_bf16 v[102:105], v[166:169], v[190:193], v[102:105]
	v_mfma_f32_16x16x32_bf16 v[94:97], v[174:177], v[190:193], v[94:97]
	v_mfma_f32_16x16x32_bf16 v[86:89], v[166:169], v[198:201], v[86:89]
	v_mfma_f32_16x16x32_bf16 v[78:81], v[174:177], v[198:201], v[78:81]
	v_mfma_f32_16x16x32_bf16 v[70:73], v[166:169], v[206:209], v[70:73]
	v_mfma_f32_16x16x32_bf16 v[66:69], v[174:177], v[206:209], v[66:69]
	s_setprio 0
	s_barrier
; #define PG8_STAGE(bufoff, gbase, voff) do { const char* gb_ = (const char*)(gbase); asm volatile("" : "+s"(gb_)); _Pragma("unroll") for (int _i = 0; _i < 2; ++_i) { unsigned vo_ = (voff)[_i]; asm volatile("" : "+v"(vo_)); \
;         __builtin_amdgcn_global_load_lds((const unsigned*)(gb_ + vo_), (PG8_LAS unsigned*)(lds + (bufoff) + ldsw + _i * 8192), 16, 0, 0); } } while (0)
; #define PG8_LDA(dst, b, h) do { _Pragma("unroll") for (int m = 0; m < 4; ++m) _Pragma("unroll") for (int k = 0; k < 2; ++k) dst[m][k] = *(const PG8_LAS bf16x8*)(lds + PG8_SA(b, h) + aoff + m * 2048 + k * 1024); } while (0)
; #define PG8_WAIT_V(n) asm volatile("s_waitcnt vmcnt(" #n ")" ::: "memory")
; #define PG8_WAIT_L(n) asm volatile("s_waitcnt lgkmcnt(" #n ")" ::: "memory")
;     ...
;             PG8_LDA(At, 1, 1); PG8_STAGE(PG8_SB(1, 0), b3, voffB); PG8_STAGE(PG8_SB(1, 1), b3 + hstepB, voffB); PG8_STAGE(PG8_SA(1, 0), a3, voffA);
;             PG8_WAIT_V(8); PG8_WAIT_L(0); PG8_BAR; PG8_MMA(1, 0, At, B0); PG8_MMA(1, 1, At, B1); PG8_BAR; PG8_SCHED;
;             } else {
;             PG8_LDB(B0, 0, 0); PG8_SCHED; PG8_LDA(At, 0, 0); PG8_STAGE(PG8_SA(1, 1), a1 + hstep, voffA);
;             PG8_WAIT_L(8); PG8_BAR; PG8_WAIT_L(0); PG8_MMA(0, 0, At, B0); PG8_BAR; PG8_SCHED;
;             PG8_LDB(B1, 0, 1); PG8_STAGE(PG8_SB(0, 0), b2, voffB);
;             PG8_BAR; PG8_WAIT_L(0); PG8_MMA(0, 1, At, B1); PG8_BAR;
;             PG8_LDA(At, 0, 1); PG8_STAGE(PG8_SA(0, 0), a2, voffA);
;             PG8_BAR; PG8_WAIT_L(0); PG8_MMA(1, 0, At, B0); PG8_BAR; PG8_SCHED;
;             PG8_STAGE(PG8_SB(0, 1), b2 + hstepB, voffB);
;             PG8_WAIT_V(6); PG8_BAR; PG8_MMA(1, 1, At, B1); PG8_BAR;
;             PG8_LDB(B0, 1, 0); PG8_SCHED; PG8_LDA(At, 1, 0); PG8_STAGE(PG8_SA(0, 1), a2 + hstep, voffA);
;             PG8_WAIT_L(8); PG8_BAR; PG8_WAIT_L(0); PG8_MMA(0, 0, At, B0); PG8_BAR; PG8_SCHED;
;             PG8_LDB(B1, 1, 1); PG8_STAGE(PG8_SB(1, 0), b3, voffB);
;             PG8_BAR; PG8_WAIT_L(0); PG8_MMA(0, 1, At, B1); PG8_BAR;
;             PG8_LDA(At, 1, 1); PG8_STAGE(PG8_SA(1, 0), a3, voffA);
;             PG8_BAR; PG8_WAIT_L(0); PG8_MMA(1, 0, At, B0); PG8_BAR; PG8_SCHED;
;             PG8_STAGE(PG8_SB(1, 1), b3 + hstepB, voffB);
;             PG8_WAIT_V(6); PG8_BAR; PG8_MMA(1, 1, At, B1); PG8_BAR;
;             }
;         }
;         if constexpr (ALIGN_EPI) { if (wr == 0) PG8_BAR; }
	s_add_u32 s18, s24, 0x80
	s_addc_u32 s19, s25, 0
	v_mov_b32_e32 v136, v138
	s_add_i32 s26, s55, s29
	ds_read_b128 v[178:181], v144 offset:49152
	ds_read_b128 v[182:185], v144 offset:50176
	ds_read_b128 v[186:189], v144 offset:51200
	ds_read_b128 v[190:193], v144 offset:52224
	ds_read_b128 v[194:197], v144 offset:53248
	ds_read_b128 v[198:201], v144 offset:54272
	ds_read_b128 v[202:205], v144 offset:55296
	ds_read_b128 v[206:209], v144 offset:56320
	s_mov_b32 m0, s26
	s_nop 0
	global_load_lds_dwordx4 v136, s[18:19]
	v_mov_b32_e32 v136, v140
	s_add_i32 m0, s26, 0x2000
	s_nop 0
	global_load_lds_dwordx4 v136, s[18:19]
	s_add_u32 s18, s24, 0x10080
	s_addc_u32 s19, s25, 0
	v_mov_b32_e32 v136, v138
	s_add_i32 s24, s56, s29
	s_mov_b32 m0, s24
	s_nop 0
	global_load_lds_dwordx4 v136, s[18:19]
	v_mov_b32_e32 v136, v140
	s_add_i32 m0, s24, 0x2000
	s_nop 0
	global_load_lds_dwordx4 v136, s[18:19]
	v_mov_b32_e32 v136, v1
	s_mov_b32 m0, s36
	s_nop 0
	global_load_lds_dwordx4 v136, s[22:23]
	v_mov_b32_e32 v136, v139
	s_mov_b32 m0, s37
	s_nop 0
	global_load_lds_dwordx4 v136, s[22:23]
	s_waitcnt vmcnt(8)
	s_waitcnt lgkmcnt(0)
	s_barrier
	s_setprio 1
	s_waitcnt lgkmcnt(0)
	v_mfma_f32_16x16x32_bf16 v[62:65], v[146:149], v[178:181], v[62:65]
	v_mfma_f32_16x16x32_bf16 v[58:61], v[154:157], v[178:181], v[58:61]
	v_mfma_f32_16x16x32_bf16 v[50:53], v[146:149], v[186:189], v[50:53]
	v_mfma_f32_16x16x32_bf16 v[42:45], v[154:157], v[186:189], v[42:45]
	v_mfma_f32_16x16x32_bf16 v[34:37], v[146:149], v[194:197], v[34:37]
	v_mfma_f32_16x16x32_bf16 v[26:29], v[154:157], v[194:197], v[26:29]
	v_mfma_f32_16x16x32_bf16 v[18:21], v[146:149], v[202:205], v[18:21]
	v_mfma_f32_16x16x32_bf16 v[10:13], v[154:157], v[202:205], v[10:13]
	v_mfma_f32_16x16x32_bf16 v[62:65], v[150:153], v[182:185], v[62:65]
	v_mfma_f32_16x16x32_bf16 v[58:61], v[158:161], v[182:185], v[58:61]
	v_mfma_f32_16x16x32_bf16 v[50:53], v[150:153], v[190:193], v[50:53]
	v_mfma_f32_16x16x32_bf16 v[42:45], v[158:161], v[190:193], v[42:45]
	v_mfma_f32_16x16x32_bf16 v[34:37], v[150:153], v[198:201], v[34:37]
	v_mfma_f32_16x16x32_bf16 v[26:29], v[158:161], v[198:201], v[26:29]
	v_mfma_f32_16x16x32_bf16 v[18:21], v[150:153], v[206:209], v[18:21]
	v_mfma_f32_16x16x32_bf16 v[10:13], v[158:161], v[206:209], v[10:13]
	s_setprio 0
	s_setprio 1
	v_mfma_f32_16x16x32_bf16 v[54:57], v[162:165], v[178:181], v[54:57]
	v_mfma_f32_16x16x32_bf16 v[46:49], v[170:173], v[178:181], v[46:49]
	v_mfma_f32_16x16x32_bf16 v[38:41], v[162:165], v[186:189], v[38:41]
	v_mfma_f32_16x16x32_bf16 v[30:33], v[170:173], v[186:189], v[30:33]
	v_mfma_f32_16x16x32_bf16 v[22:25], v[162:165], v[194:197], v[22:25]
	v_mfma_f32_16x16x32_bf16 v[14:17], v[170:173], v[194:197], v[14:17]
	v_mfma_f32_16x16x32_bf16 v[6:9], v[162:165], v[202:205], v[6:9]
	v_mfma_f32_16x16x32_bf16 v[2:5], v[170:173], v[202:205], v[2:5]
	v_mfma_f32_16x16x32_bf16 v[54:57], v[166:169], v[182:185], v[54:57]
	v_mfma_f32_16x16x32_bf16 v[46:49], v[174:177], v[182:185], v[46:49]
	v_mfma_f32_16x16x32_bf16 v[38:41], v[166:169], v[190:193], v[38:41]
	v_mfma_f32_16x16x32_bf16 v[30:33], v[174:177], v[190:193], v[30:33]
	v_mfma_f32_16x16x32_bf16 v[22:25], v[166:169], v[198:201], v[22:25]
	v_mfma_f32_16x16x32_bf16 v[14:17], v[174:177], v[198:201], v[14:17]
	v_mfma_f32_16x16x32_bf16 v[6:9], v[166:169], v[206:209], v[6:9]
	v_mfma_f32_16x16x32_bf16 v[2:5], v[174:177], v[206:209], v[2:5]
	s_setprio 0
	s_barrier
	s_add_i32 s54, s54, 2
	s_add_u32 s52, s52, 0x100
	s_addc_u32 s53, s53, 0
	s_cmp_gt_u32 s54, 13
	s_mov_b64 s[18:19], s[20:21]
	s_cbranch_scc0 .LBB0_895
	s_and_b64 vcc, exec, s[2:3]
	s_cbranch_vccz .LBB0_898
	s_barrier

; #define PG8_STAGE(bufoff, gbase, voff) do { const char* gb_ = (const char*)(gbase); asm volatile("" : "+s"(gb_)); _Pragma("unroll") for (int _i = 0; _i < 2; ++_i) { unsigned vo_ = (voff)[_i]; asm volatile("" : "+v"(vo_)); \
;         __builtin_amdgcn_global_load_lds((const unsigned*)(gb_ + vo_), (PG8_LAS unsigned*)(lds + (bufoff) + ldsw + _i * 8192), 16, 0, 0); } } while (0)
; #define PG8_LDA(dst, b, h) do { _Pragma("unroll") for (int m = 0; m < 4; ++m) _Pragma("unroll") for (int k = 0; k < 2; ++k) dst[m][k] = *(const PG8_LAS bf16x8*)(lds + PG8_SA(b, h) + aoff + m * 2048 + k * 1024); } while (0)
; #define PG8_LDB(dst, b, h) do { _Pragma("unroll") for (int n = 0; n < 2; ++n) _Pragma("unroll") for (int k = 0; k < 2; ++k) dst[n][k] = *(const PG8_LAS bf16x8*)(lds + PG8_SB(b, h) + boff + n * 2048 + k * 1024); } while (0)
; #define PG8_MMA(ai, bj, At, Bt) do { __builtin_amdgcn_s_setprio(1); _Pragma("unroll") for (int m = 0; m < 4; ++m) _Pragma("unroll") for (int n = 0; n < 2; ++n) _Pragma("unroll") for (int k = 0; k < 2; ++k) \
;         acc[ai][bj][m][n] = __builtin_amdgcn_mfma_f32_16x16x32_bf16(Bt[n][k], At[m][k], acc[ai][bj][m][n], 0, 0, 0); __builtin_amdgcn_s_setprio(0); } while (0)
; #define PG8_WAIT_V(n) asm volatile("s_waitcnt vmcnt(" #n ")" ::: "memory")
; #define PG8_WAIT_L(n) asm volatile("s_waitcnt lgkmcnt(" #n ")" ::: "memory")
; #define PG8_BAR __builtin_amdgcn_s_barrier()
; #define PG8_SCHED __builtin_amdgcn_sched_barrier(0)
;     ...
;         for (int t = 0; t < nt; t += 2) {
;             const bool last = (t == nt - 2);
;             if (GP && t == 2) gp1 = __builtin_amdgcn_s_memrealtime();
;             const char* a1 = cA + (size_t)(t + 1) * kstep;
;             const char* a2 = last ? nA : cA + (size_t)(t + 2) * kstep; const char* b2 = last ? nB : cB + (size_t)(t + 2) * kstep;
;             const char* a3 = a2 + kstep; const char* b3 = b2 + kstep;
;             if (last && has_next) S.a_ready(nxt);
;             if constexpr (SP2) {
;             PG8_LDB(B0, 0, 0); PG8_LDB(B1, 0, 1); PG8_SCHED; PG8_LDA(At, 0, 0); PG8_STAGE(PG8_SA(1, 1), a1 + hstep, voffA);
;             PG8_WAIT_V(8); PG8_WAIT_L(0); PG8_BAR; PG8_MMA(0, 0, At, B0); PG8_MMA(0, 1, At, B1); PG8_BAR; PG8_SCHED;
;             PG8_LDA(At, 0, 1); PG8_STAGE(PG8_SB(0, 0), b2, voffB); PG8_STAGE(PG8_SB(0, 1), b2 + hstepB, voffB); PG8_STAGE(PG8_SA(0, 0), a2, voffA);
.LBB0_974:
	s_add_u32 s47, s12, s20
	s_addc_u32 s49, s13, s21
	s_add_u32 s22, s47, 0x100
	s_addc_u32 s23, s49, 0
	v_add_u32_e32 v152, s41, v138
	v_add_u32_e32 v168, s42, v138
	s_add_u32 s24, s10, s20
	ds_read_b128 v[140:143], v152
	ds_read_b128 v[144:147], v152 offset:1024
	ds_read_b128 v[148:151], v152 offset:2048
	ds_read_b128 v[152:155], v152 offset:3072
	ds_read_b128 v[156:159], v168
	ds_read_b128 v[160:163], v168 offset:1024
	ds_read_b128 v[164:167], v168 offset:2048
	ds_read_b128 v[168:171], v168 offset:3072
	s_addc_u32 s25, s11, s21
	s_add_u32 s24, s24, 0x100
	s_addc_u32 s25, s25, 0
	s_cmp_eq_u32 s46, 60
	s_cselect_b32 s26, s44, s22
	s_cselect_b32 s27, s17, s23
	s_cselect_b32 s24, s45, s24
	s_cselect_b32 s25, s15, s25
	s_add_u32 s22, s26, 0x80
	s_addc_u32 s23, s27, 0
	s_add_u32 s48, s47, 0x100080
	s_addc_u32 s49, s49, 0
	v_mov_b32_e32 v204, v133
	s_waitcnt lgkmcnt(7)
	ds_read_b128 v[172:175], v139
	ds_read_b128 v[176:179], v139 offset:1024
	ds_read_b128 v[180:183], v139 offset:2048
	ds_read_b128 v[184:187], v139 offset:3072
	ds_read_b128 v[188:191], v139 offset:4096
	ds_read_b128 v[192:195], v139 offset:5120
	ds_read_b128 v[196:199], v139 offset:6144
	ds_read_b128 v[200:203], v139 offset:7168
	s_add_i32 m0, s7, 0xc000
	s_nop 0
	global_load_lds_dwordx4 v204, s[48:49]
	v_mov_b32_e32 v204, v135
	s_add_i32 m0, s7, 0xe000
	s_nop 0
	global_load_lds_dwordx4 v204, s[48:49]
	s_waitcnt vmcnt(8)
	s_waitcnt lgkmcnt(0)
	s_barrier
	s_setprio 1
	s_waitcnt lgkmcnt(0)
	v_mfma_f32_16x16x32_bf16 v[124:127], v[140:143], v[172:175], v[124:127]
	v_mfma_f32_16x16x32_bf16 v[120:123], v[148:151], v[172:175], v[120:123]
	v_mfma_f32_16x16x32_bf16 v[108:111], v[140:143], v[180:183], v[108:111]
	v_mfma_f32_16x16x32_bf16 v[104:107], v[148:151], v[180:183], v[104:107]
	v_mfma_f32_16x16x32_bf16 v[92:95], v[140:143], v[188:191], v[92:95]
	v_mfma_f32_16x16x32_bf16 v[88:91], v[148:151], v[188:191], v[88:91]
	v_mfma_f32_16x16x32_bf16 v[76:79], v[140:143], v[196:199], v[76:79]
	v_mfma_f32_16x16x32_bf16 v[72:75], v[148:151], v[196:199], v[72:75]
	v_mfma_f32_16x16x32_bf16 v[124:127], v[144:147], v[176:179], v[124:127]
	v_mfma_f32_16x16x32_bf16 v[120:123], v[152:155], v[176:179], v[120:123]
	v_mfma_f32_16x16x32_bf16 v[108:111], v[144:147], v[184:187], v[108:111]
	v_mfma_f32_16x16x32_bf16 v[104:107], v[152:155], v[184:187], v[104:107]
	v_mfma_f32_16x16x32_bf16 v[92:95], v[144:147], v[192:195], v[92:95]
	v_mfma_f32_16x16x32_bf16 v[88:91], v[152:155], v[192:195], v[88:91]
	v_mfma_f32_16x16x32_bf16 v[76:79], v[144:147], v[200:203], v[76:79]
	v_mfma_f32_16x16x32_bf16 v[72:75], v[152:155], v[200:203], v[72:75]
	s_setprio 0
	s_setprio 1
	v_mfma_f32_16x16x32_bf16 v[116:119], v[156:159], v[172:175], v[116:119]
	v_mfma_f32_16x16x32_bf16 v[112:115], v[164:167], v[172:175], v[112:115]
	v_mfma_f32_16x16x32_bf16 v[100:103], v[156:159], v[180:183], v[100:103]
	v_mfma_f32_16x16x32_bf16 v[96:99], v[164:167], v[180:183], v[96:99]
	v_mfma_f32_16x16x32_bf16 v[84:87], v[156:159], v[188:191], v[84:87]
	v_mfma_f32_16x16x32_bf16 v[80:83], v[164:167], v[188:191], v[80:83]
	v_mfma_f32_16x16x32_bf16 v[68:71], v[156:159], v[196:199], v[68:71]
	v_mfma_f32_16x16x32_bf16 v[64:67], v[164:167], v[196:199], v[64:67]
	v_mfma_f32_16x16x32_bf16 v[116:119], v[160:163], v[176:179], v[116:119]
	v_mfma_f32_16x16x32_bf16 v[112:115], v[168:171], v[176:179], v[112:115]
	v_mfma_f32_16x16x32_bf16 v[100:103], v[160:163], v[184:187], v[100:103]
	v_mfma_f32_16x16x32_bf16 v[96:99], v[168:171], v[184:187], v[96:99]
	v_mfma_f32_16x16x32_bf16 v[84:87], v[160:163], v[192:195], v[84:87]
	v_mfma_f32_16x16x32_bf16 v[80:83], v[168:171], v[192:195], v[80:83]
	v_mfma_f32_16x16x32_bf16 v[68:71], v[160:163], v[200:203], v[68:71]
	v_mfma_f32_16x16x32_bf16 v[64:67], v[168:171], v[200:203], v[64:67]
	s_setprio 0
	s_barrier
	s_mov_b64 s[48:49], s[24:25]
	v_mov_b32_e32 v204, v134
	s_add_i32 s47, s41, s30
	ds_read_b128 v[172:175], v139 offset:16384
	ds_read_b128 v[176:179], v139 offset:17408
	ds_read_b128 v[180:183], v139 offset:18432
	ds_read_b128 v[184:187], v139 offset:19456
	ds_read_b128 v[188:191], v139 offset:20480
	ds_read_b128 v[192:195], v139 offset:21504
	ds_read_b128 v[196:199], v139 offset:22528
	ds_read_b128 v[200:203], v139 offset:23552
	s_mov_b32 m0, s47
	s_nop 0
	global_load_lds_dwordx4 v204, s[48:49]
	v_mov_b32_e32 v204, v136
	s_add_i32 m0, s47, 0x2000
	s_nop 0
	global_load_lds_dwordx4 v204, s[48:49]
	s_add_u32 s48, s24, 0x100000
	s_addc_u32 s49, s25, 0
	v_mov_b32_e32 v204, v134
	s_add_i32 s47, s42, s30
	s_mov_b32 m0, s47
	s_nop 0
	global_load_lds_dwordx4 v204, s[48:49]
	v_mov_b32_e32 v204, v136
	s_add_i32 m0, s47, 0x2000
	s_nop 0
	global_load_lds_dwordx4 v204, s[48:49]
	s_mov_b64 s[48:49], s[26:27]
	v_mov_b32_e32 v204, v133
	s_mov_b32 m0, s7
	s_nop 0
	global_load_lds_dwordx4 v204, s[48:49]
	v_mov_b32_e32 v204, v135
	s_mov_b32 m0, s31
	s_nop 0
	global_load_lds_dwordx4 v204, s[48:49]
	s_waitcnt vmcnt(8)
	s_waitcnt lgkmcnt(0)
	s_barrier
; #define PG8_STAGE(bufoff, gbase, voff) do { const char* gb_ = (const char*)(gbase); asm volatile("" : "+s"(gb_)); _Pragma("unroll") for (int _i = 0; _i < 2; ++_i) { unsigned vo_ = (voff)[_i]; asm volatile("" : "+v"(vo_)); \
;         __builtin_amdgcn_global_load_lds((const unsigned*)(gb_ + vo_), (PG8_LAS unsigned*)(lds + (bufoff) + ldsw + _i * 8192), 16, 0, 0); } } while (0)
; #define PG8_LDA(dst, b, h) do { _Pragma("unroll") for (int m = 0; m < 4; ++m) _Pragma("unroll") for (int k = 0; k < 2; ++k) dst[m][k] = *(const PG8_LAS bf16x8*)(lds + PG8_SA(b, h) + aoff + m * 2048 + k * 1024); } while (0)
; #define PG8_LDB(dst, b, h) do { _Pragma("unroll") for (int n = 0; n < 2; ++n) _Pragma("unroll") for (int k = 0; k < 2; ++k) dst[n][k] = *(const PG8_LAS bf16x8*)(lds + PG8_SB(b, h) + boff + n * 2048 + k * 1024); } while (0)
; #define PG8_MMA(ai, bj, At, Bt) do { __builtin_amdgcn_s_setprio(1); _Pragma("unroll") for (int m = 0; m < 4; ++m) _Pragma("unroll") for (int n = 0; n < 2; ++n) _Pragma("unroll") for (int k = 0; k < 2; ++k) \
;         acc[ai][bj][m][n] = __builtin_amdgcn_mfma_f32_16x16x32_bf16(Bt[n][k], At[m][k], acc[ai][bj][m][n], 0, 0, 0); __builtin_amdgcn_s_setprio(0); } while (0)
; #define PG8_WAIT_V(n) asm volatile("s_waitcnt vmcnt(" #n ")" ::: "memory")
; #define PG8_WAIT_L(n) asm volatile("s_waitcnt lgkmcnt(" #n ")" ::: "memory")
; #define PG8_BAR __builtin_amdgcn_s_barrier()
; #define PG8_SCHED __builtin_amdgcn_sched_barrier(0)
;     ...
;             PG8_WAIT_V(8); PG8_WAIT_L(0); PG8_BAR; PG8_MMA(1, 0, At, B0); PG8_MMA(1, 1, At, B1); PG8_BAR; PG8_SCHED;
;             PG8_LDB(B0, 1, 0); PG8_LDB(B1, 1, 1); PG8_SCHED; PG8_LDA(At, 1, 0); PG8_STAGE(PG8_SA(0, 1), a2 + hstep, voffA);
;             PG8_WAIT_V(8); PG8_WAIT_L(0); PG8_BAR; PG8_MMA(0, 0, At, B0); PG8_MMA(0, 1, At, B1); PG8_BAR; PG8_SCHED;
	s_setprio 1
	s_waitcnt lgkmcnt(0)
	v_mfma_f32_16x16x32_bf16 v[60:63], v[140:143], v[172:175], v[60:63]
	v_mfma_f32_16x16x32_bf16 v[56:59], v[148:151], v[172:175], v[56:59]
	v_mfma_f32_16x16x32_bf16 v[44:47], v[140:143], v[180:183], v[44:47]
	v_mfma_f32_16x16x32_bf16 v[40:43], v[148:151], v[180:183], v[40:43]
	v_mfma_f32_16x16x32_bf16 v[28:31], v[140:143], v[188:191], v[28:31]
	v_mfma_f32_16x16x32_bf16 v[24:27], v[148:151], v[188:191], v[24:27]
	v_mfma_f32_16x16x32_bf16 v[12:15], v[140:143], v[196:199], v[12:15]
	v_mfma_f32_16x16x32_bf16 v[8:11], v[148:151], v[196:199], v[8:11]
	v_mfma_f32_16x16x32_bf16 v[60:63], v[144:147], v[176:179], v[60:63]
	v_mfma_f32_16x16x32_bf16 v[56:59], v[152:155], v[176:179], v[56:59]
	v_mfma_f32_16x16x32_bf16 v[44:47], v[144:147], v[184:187], v[44:47]
	v_mfma_f32_16x16x32_bf16 v[40:43], v[152:155], v[184:187], v[40:43]
	v_mfma_f32_16x16x32_bf16 v[28:31], v[144:147], v[192:195], v[28:31]
	v_mfma_f32_16x16x32_bf16 v[24:27], v[152:155], v[192:195], v[24:27]
	v_mfma_f32_16x16x32_bf16 v[12:15], v[144:147], v[200:203], v[12:15]
	v_mfma_f32_16x16x32_bf16 v[8:11], v[152:155], v[200:203], v[8:11]
	s_setprio 0
	s_setprio 1
	v_mfma_f32_16x16x32_bf16 v[52:55], v[156:159], v[172:175], v[52:55]
	v_mfma_f32_16x16x32_bf16 v[48:51], v[164:167], v[172:175], v[48:51]
	v_mfma_f32_16x16x32_bf16 v[36:39], v[156:159], v[180:183], v[36:39]
	v_mfma_f32_16x16x32_bf16 v[32:35], v[164:167], v[180:183], v[32:35]
	v_mfma_f32_16x16x32_bf16 v[20:23], v[156:159], v[188:191], v[20:23]
	v_mfma_f32_16x16x32_bf16 v[16:19], v[164:167], v[188:191], v[16:19]
	v_mfma_f32_16x16x32_bf16 v[4:7], v[156:159], v[196:199], v[4:7]
	v_mfma_f32_16x16x32_bf16 v[0:3], v[164:167], v[196:199], v[0:3]
	v_mfma_f32_16x16x32_bf16 v[52:55], v[160:163], v[176:179], v[52:55]
	v_mfma_f32_16x16x32_bf16 v[48:51], v[168:171], v[176:179], v[48:51]
	v_mfma_f32_16x16x32_bf16 v[36:39], v[160:163], v[184:187], v[36:39]
	v_mfma_f32_16x16x32_bf16 v[32:35], v[168:171], v[184:187], v[32:35]
	v_mfma_f32_16x16x32_bf16 v[20:23], v[160:163], v[192:195], v[20:23]
	v_mfma_f32_16x16x32_bf16 v[16:19], v[168:171], v[192:195], v[16:19]
	v_mfma_f32_16x16x32_bf16 v[4:7], v[160:163], v[200:203], v[4:7]
	v_mfma_f32_16x16x32_bf16 v[0:3], v[168:171], v[200:203], v[0:3]
	s_setprio 0
	s_barrier
	s_add_i32 s47, 0, 0x18000
	s_add_i32 s48, 0, 0x1c000
	v_add_u32_e32 v152, s47, v138
	v_add_u32_e32 v168, s48, v138
	ds_read_b128 v[140:143], v152
	ds_read_b128 v[144:147], v152 offset:1024
	ds_read_b128 v[148:151], v152 offset:2048
	ds_read_b128 v[152:155], v152 offset:3072
	ds_read_b128 v[156:159], v168
	ds_read_b128 v[160:163], v168 offset:1024
	ds_read_b128 v[164:167], v168 offset:2048
	ds_read_b128 v[168:171], v168 offset:3072
	s_add_u32 s26, s26, 0x100000
	s_addc_u32 s27, s27, 0
	v_mov_b32_e32 v204, v133
	s_mov_b32 m0, s33
	ds_read_b128 v[172:175], v139 offset:32768
	ds_read_b128 v[176:179], v139 offset:33792
	ds_read_b128 v[180:183], v139 offset:34816
	ds_read_b128 v[184:187], v139 offset:35840
	ds_read_b128 v[188:191], v139 offset:36864
	ds_read_b128 v[192:195], v139 offset:37888
	ds_read_b128 v[196:199], v139 offset:38912
	ds_read_b128 v[200:203], v139 offset:39936
	s_nop 0
	global_load_lds_dwordx4 v204, s[26:27]
	v_mov_b32_e32 v204, v135
	s_mov_b32 m0, s35
	s_nop 0
	global_load_lds_dwordx4 v204, s[26:27]
	s_waitcnt vmcnt(8)
	s_waitcnt lgkmcnt(0)
	s_barrier
	s_setprio 1
	s_waitcnt lgkmcnt(0)
	v_mfma_f32_16x16x32_bf16 v[124:127], v[140:143], v[172:175], v[124:127]
	v_mfma_f32_16x16x32_bf16 v[120:123], v[148:151], v[172:175], v[120:123]
	v_mfma_f32_16x16x32_bf16 v[108:111], v[140:143], v[180:183], v[108:111]
	v_mfma_f32_16x16x32_bf16 v[104:107], v[148:151], v[180:183], v[104:107]
	v_mfma_f32_16x16x32_bf16 v[92:95], v[140:143], v[188:191], v[92:95]
	v_mfma_f32_16x16x32_bf16 v[88:91], v[148:151], v[188:191], v[88:91]
	v_mfma_f32_16x16x32_bf16 v[76:79], v[140:143], v[196:199], v[76:79]
	v_mfma_f32_16x16x32_bf16 v[72:75], v[148:151], v[196:199], v[72:75]
	v_mfma_f32_16x16x32_bf16 v[124:127], v[144:147], v[176:179], v[124:127]
	v_mfma_f32_16x16x32_bf16 v[120:123], v[152:155], v[176:179], v[120:123]
	v_mfma_f32_16x16x32_bf16 v[108:111], v[144:147], v[184:187], v[108:111]
	v_mfma_f32_16x16x32_bf16 v[104:107], v[152:155], v[184:187], v[104:107]
	v_mfma_f32_16x16x32_bf16 v[92:95], v[144:147], v[192:195], v[92:95]
	v_mfma_f32_16x16x32_bf16 v[88:91], v[152:155], v[192:195], v[88:91]
	v_mfma_f32_16x16x32_bf16 v[76:79], v[144:147], v[200:203], v[76:79]
	v_mfma_f32_16x16x32_bf16 v[72:75], v[152:155], v[200:203], v[72:75]
	s_setprio 0
	s_setprio 1
	v_mfma_f32_16x16x32_bf16 v[116:119], v[156:159], v[172:175], v[116:119]
	v_mfma_f32_16x16x32_bf16 v[112:115], v[164:167], v[172:175], v[112:115]
	v_mfma_f32_16x16x32_bf16 v[100:103], v[156:159], v[180:183], v[100:103]
	v_mfma_f32_16x16x32_bf16 v[96:99], v[164:167], v[180:183], v[96:99]
	v_mfma_f32_16x16x32_bf16 v[84:87], v[156:159], v[188:191], v[84:87]
	v_mfma_f32_16x16x32_bf16 v[80:83], v[164:167], v[188:191], v[80:83]
	v_mfma_f32_16x16x32_bf16 v[68:71], v[156:159], v[196:199], v[68:71]
	v_mfma_f32_16x16x32_bf16 v[64:67], v[164:167], v[196:199], v[64:67]
	v_mfma_f32_16x16x32_bf16 v[116:119], v[160:163], v[176:179], v[116:119]
	v_mfma_f32_16x16x32_bf16 v[112:115], v[168:171], v[176:179], v[112:115]
	v_mfma_f32_16x16x32_bf16 v[100:103], v[160:163], v[184:187], v[100:103]
	v_mfma_f32_16x16x32_bf16 v[96:99], v[168:171], v[184:187], v[96:99]
	v_mfma_f32_16x16x32_bf16 v[84:87], v[160:163], v[192:195], v[84:87]
	v_mfma_f32_16x16x32_bf16 v[80:83], v[168:171], v[192:195], v[80:83]
	v_mfma_f32_16x16x32_bf16 v[68:71], v[160:163], v[200:203], v[68:71]
	v_mfma_f32_16x16x32_bf16 v[64:67], v[168:171], v[200:203], v[64:67]
	s_setprio 0
	s_barrier
;     ...
;             PG8_LDA(At, 1, 1); PG8_STAGE(PG8_SB(1, 0), b3, voffB); PG8_STAGE(PG8_SB(1, 1), b3 + hstepB, voffB); PG8_STAGE(PG8_SA(1, 0), a3, voffA);
;             PG8_WAIT_V(8); PG8_WAIT_L(0); PG8_BAR; PG8_MMA(1, 0, At, B0); PG8_MMA(1, 1, At, B1); PG8_BAR; PG8_SCHED;
;             } else {
;             PG8_LDB(B0, 0, 0); PG8_SCHED; PG8_LDA(At, 0, 0); PG8_STAGE(PG8_SA(1, 1), a1 + hstep, voffA);
;             PG8_WAIT_L(8); PG8_BAR; PG8_WAIT_L(0); PG8_MMA(0, 0, At, B0); PG8_BAR; PG8_SCHED;
;             PG8_LDB(B1, 0, 1); PG8_STAGE(PG8_SB(0, 0), b2, voffB);
;             PG8_BAR; PG8_WAIT_L(0); PG8_MMA(0, 1, At, B1); PG8_BAR;
;             PG8_LDA(At, 0, 1); PG8_STAGE(PG8_SA(0, 0), a2, voffA);
;             PG8_BAR; PG8_WAIT_L(0); PG8_MMA(1, 0, At, B0); PG8_BAR; PG8_SCHED;
;             PG8_STAGE(PG8_SB(0, 1), b2 + hstepB, voffB);
;             PG8_WAIT_V(6); PG8_BAR; PG8_MMA(1, 1, At, B1); PG8_BAR;
;             PG8_LDB(B0, 1, 0); PG8_SCHED; PG8_LDA(At, 1, 0); PG8_STAGE(PG8_SA(0, 1), a2 + hstep, voffA);
;             PG8_WAIT_L(8); PG8_BAR; PG8_WAIT_L(0); PG8_MMA(0, 0, At, B0); PG8_BAR; PG8_SCHED;
;             PG8_LDB(B1, 1, 1); PG8_STAGE(PG8_SB(1, 0), b3, voffB);
;             PG8_BAR; PG8_WAIT_L(0); PG8_MMA(0, 1, At, B1); PG8_BAR;
;             PG8_LDA(At, 1, 1); PG8_STAGE(PG8_SA(1, 0), a3, voffA);
;             PG8_BAR; PG8_WAIT_L(0); PG8_MMA(1, 0, At, B0); PG8_BAR; PG8_SCHED;
;             PG8_STAGE(PG8_SB(1, 1), b3 + hstepB, voffB);
;             PG8_WAIT_V(6); PG8_BAR; PG8_MMA(1, 1, At, B1); PG8_BAR;
;             }
;         }
;         if constexpr (ALIGN_EPI) { if (wr == 0) PG8_BAR; }
;         if (GP) { gpEnd = __builtin_amdgcn_s_memrealtime(); if (ui == 0) accFirst0 += gp1 - gpU; else accFirst += gp1 - gpU; accSteady += gpEnd - gp1; }
;         if constexpr (!Epi::AFTER_DRAIN) { E(acc, cur, wr, wc, fr, fq); S.done(cur); }
;         if (GP) accE += __builtin_amdgcn_s_memrealtime() - gpEnd;
;         if (!has_next) break;
;         if constexpr (!Epi::KEEP_ACC) {
; #pragma unroll
;         for (int a = 0; a < 2; ++a)
; #pragma unroll
;             for (int b = 0; b < 2; ++b)
; #pragma unroll
;                 for (int m = 0; m < 4; ++m)
; #pragma unroll
;                     for (int n = 0; n < 2; ++n) acc[a][b][m][n] = (f32x4){0.f, 0.f, 0.f, 0.f};
;         }
;         cur = nxt; cA = nA; cB = nB; ++ui;
	s_add_u32 s26, s24, 0x80
	s_addc_u32 s27, s25, 0
	v_mov_b32_e32 v204, v134
	s_add_i32 s47, s47, s30
	ds_read_b128 v[172:175], v139 offset:49152
	ds_read_b128 v[176:179], v139 offset:50176
	ds_read_b128 v[180:183], v139 offset:51200
	ds_read_b128 v[184:187], v139 offset:52224
	ds_read_b128 v[188:191], v139 offset:53248
	ds_read_b128 v[192:195], v139 offset:54272
	ds_read_b128 v[196:199], v139 offset:55296
	ds_read_b128 v[200:203], v139 offset:56320
	s_mov_b32 m0, s47
	s_nop 0
	global_load_lds_dwordx4 v204, s[26:27]
	v_mov_b32_e32 v204, v136
	s_add_i32 m0, s47, 0x2000
	s_add_u32 s24, s24, 0x100080
	global_load_lds_dwordx4 v204, s[26:27]
	s_addc_u32 s25, s25, 0
	v_mov_b32_e32 v204, v134
	s_add_i32 s26, s48, s30
	s_mov_b32 m0, s26
	s_nop 0
	global_load_lds_dwordx4 v204, s[24:25]
	v_mov_b32_e32 v204, v136
	s_add_i32 m0, s26, 0x2000
	s_nop 0
	global_load_lds_dwordx4 v204, s[24:25]
	v_mov_b32_e32 v204, v133
	s_mov_b32 m0, s39
	s_nop 0
	global_load_lds_dwordx4 v204, s[22:23]
	v_mov_b32_e32 v204, v135
	s_mov_b32 m0, s40
	s_nop 0
	global_load_lds_dwordx4 v204, s[22:23]
	s_waitcnt vmcnt(8)
	s_waitcnt lgkmcnt(0)
	s_barrier
	s_setprio 1
	s_waitcnt lgkmcnt(0)
	v_mfma_f32_16x16x32_bf16 v[60:63], v[140:143], v[172:175], v[60:63]
	v_mfma_f32_16x16x32_bf16 v[56:59], v[148:151], v[172:175], v[56:59]
	v_mfma_f32_16x16x32_bf16 v[44:47], v[140:143], v[180:183], v[44:47]
	v_mfma_f32_16x16x32_bf16 v[40:43], v[148:151], v[180:183], v[40:43]
	v_mfma_f32_16x16x32_bf16 v[28:31], v[140:143], v[188:191], v[28:31]
	v_mfma_f32_16x16x32_bf16 v[24:27], v[148:151], v[188:191], v[24:27]
	v_mfma_f32_16x16x32_bf16 v[12:15], v[140:143], v[196:199], v[12:15]
	v_mfma_f32_16x16x32_bf16 v[8:11], v[148:151], v[196:199], v[8:11]
	v_mfma_f32_16x16x32_bf16 v[60:63], v[144:147], v[176:179], v[60:63]
	v_mfma_f32_16x16x32_bf16 v[56:59], v[152:155], v[176:179], v[56:59]
	v_mfma_f32_16x16x32_bf16 v[44:47], v[144:147], v[184:187], v[44:47]
	v_mfma_f32_16x16x32_bf16 v[40:43], v[152:155], v[184:187], v[40:43]
	v_mfma_f32_16x16x32_bf16 v[28:31], v[144:147], v[192:195], v[28:31]
	v_mfma_f32_16x16x32_bf16 v[24:27], v[152:155], v[192:195], v[24:27]
	v_mfma_f32_16x16x32_bf16 v[12:15], v[144:147], v[200:203], v[12:15]
	v_mfma_f32_16x16x32_bf16 v[8:11], v[152:155], v[200:203], v[8:11]
	s_setprio 0
	s_setprio 1
	v_mfma_f32_16x16x32_bf16 v[52:55], v[156:159], v[172:175], v[52:55]
	v_mfma_f32_16x16x32_bf16 v[48:51], v[164:167], v[172:175], v[48:51]
	v_mfma_f32_16x16x32_bf16 v[36:39], v[156:159], v[180:183], v[36:39]
	v_mfma_f32_16x16x32_bf16 v[32:35], v[164:167], v[180:183], v[32:35]
	v_mfma_f32_16x16x32_bf16 v[20:23], v[156:159], v[188:191], v[20:23]
	v_mfma_f32_16x16x32_bf16 v[16:19], v[164:167], v[188:191], v[16:19]
	v_mfma_f32_16x16x32_bf16 v[4:7], v[156:159], v[196:199], v[4:7]
	v_mfma_f32_16x16x32_bf16 v[0:3], v[164:167], v[196:199], v[0:3]
	v_mfma_f32_16x16x32_bf16 v[52:55], v[160:163], v[176:179], v[52:55]
	v_mfma_f32_16x16x32_bf16 v[48:51], v[168:171], v[176:179], v[48:51]
	v_mfma_f32_16x16x32_bf16 v[36:39], v[160:163], v[184:187], v[36:39]
	v_mfma_f32_16x16x32_bf16 v[32:35], v[168:171], v[184:187], v[32:35]
	v_mfma_f32_16x16x32_bf16 v[20:23], v[160:163], v[192:195], v[20:23]
	v_mfma_f32_16x16x32_bf16 v[16:19], v[168:171], v[192:195], v[16:19]
	v_mfma_f32_16x16x32_bf16 v[4:7], v[160:163], v[200:203], v[4:7]
	v_mfma_f32_16x16x32_bf16 v[0:3], v[168:171], v[200:203], v[0:3]
	s_setprio 0
	s_barrier
	s_add_i32 s46, s46, 2
	s_add_u32 s20, s20, 0x100
	s_addc_u32 s21, s21, 0
	s_cmp_gt_u32 s46, 61
	s_cbranch_scc0 .LBB0_974
	s_andn2_b64 vcc, exec, s[4:5]
	s_cbranch_vccnz .LBB0_966
	v_mov_b32_e32 v0, 0
	s_mov_b32 s34, s14
	s_mov_b32 s6, s16
	s_mov_b64 s[10:11], s[18:19]
	s_mov_b64 s[12:13], s[2:3]
	s_mov_b32 s38, s43
	v_mov_b32_e32 v1, v0
	v_mov_b32_e32 v2, v0
	v_mov_b32_e32 v3, v0
	v_mov_b32_e32 v4, v0
	v_mov_b32_e32 v5, v0
	v_mov_b32_e32 v6, v0
	v_mov_b32_e32 v7, v0
	v_mov_b32_e32 v16, v0
	v_mov_b32_e32 v17, v0
	v_mov_b32_e32 v18, v0
	v_mov_b32_e32 v19, v0
	v_mov_b32_e32 v20, v0
	v_mov_b32_e32 v21, v0
	v_mov_b32_e32 v22, v0
	v_mov_b32_e32 v23, v0
	v_mov_b32_e32 v32, v0
	v_mov_b32_e32 v33, v0
	v_mov_b32_e32 v34, v0
	v_mov_b32_e32 v35, v0
	v_mov_b32_e32 v36, v0
	v_mov_b32_e32 v37, v0
	v_mov_b32_e32 v38, v0
	v_mov_b32_e32 v39, v0
	v_mov_b32_e32 v48, v0
	v_mov_b32_e32 v49, v0
	v_mov_b32_e32 v50, v0
	v_mov_b32_e32 v51, v0
	v_mov_b32_e32 v52, v0
	v_mov_b32_e32 v53, v0
	v_mov_b32_e32 v54, v0
	v_mov_b32_e32 v55, v0
	v_mov_b32_e32 v8, v0
	v_mov_b32_e32 v9, v0
	v_mov_b32_e32 v10, v0
	v_mov_b32_e32 v11, v0
	v_mov_b32_e32 v12, v0
	v_mov_b32_e32 v13, v0
	v_mov_b32_e32 v14, v0
	v_mov_b32_e32 v15, v0
	v_mov_b32_e32 v24, v0
	v_mov_b32_e32 v25, v0
	v_mov_b32_e32 v26, v0
	v_mov_b32_e32 v27, v0
	v_mov_b32_e32 v28, v0
	v_mov_b32_e32 v29, v0
	v_mov_b32_e32 v30, v0
	v_mov_b32_e32 v31, v0
	v_mov_b32_e32 v40, v0
	v_mov_b32_e32 v41, v0
	v_mov_b32_e32 v42, v0
	v_mov_b32_e32 v43, v0
	v_mov_b32_e32 v44, v0
	v_mov_b32_e32 v45, v0
	v_mov_b32_e32 v46, v0
	v_mov_b32_e32 v47, v0
	v_mov_b32_e32 v56, v0
	v_mov_b32_e32 v57, v0
	v_mov_b32_e32 v58, v0
	v_mov_b32_e32 v59, v0
	v_mov_b32_e32 v60, v0
	v_mov_b32_e32 v61, v0
	v_mov_b32_e32 v62, v0
	v_mov_b32_e32 v63, v0
	v_mov_b32_e32 v64, v0
	v_mov_b32_e32 v65, v0
	v_mov_b32_e32 v66, v0
	v_mov_b32_e32 v67, v0
	v_mov_b32_e32 v68, v0
	v_mov_b32_e32 v69, v0
	v_mov_b32_e32 v70, v0
	v_mov_b32_e32 v71, v0
	v_mov_b32_e32 v80, v0
	v_mov_b32_e32 v81, v0
	v_mov_b32_e32 v82, v0
	v_mov_b32_e32 v83, v0
	v_mov_b32_e32 v84, v0
	v_mov_b32_e32 v85, v0
	v_mov_b32_e32 v86, v0
	v_mov_b32_e32 v87, v0
	v_mov_b32_e32 v96, v0
	v_mov_b32_e32 v97, v0
	v_mov_b32_e32 v98, v0
	v_mov_b32_e32 v99, v0
	v_mov_b32_e32 v100, v0
	v_mov_b32_e32 v101, v0
	v_mov_b32_e32 v102, v0
	v_mov_b32_e32 v103, v0
	v_mov_b32_e32 v112, v0
	v_mov_b32_e32 v113, v0
	v_mov_b32_e32 v114, v0
	v_mov_b32_e32 v115, v0
	v_mov_b32_e32 v116, v0
	v_mov_b32_e32 v117, v0
	v_mov_b32_e32 v118, v0
	v_mov_b32_e32 v119, v0
	v_mov_b32_e32 v72, v0
	v_mov_b32_e32 v73, v0
	v_mov_b32_e32 v74, v0
	v_mov_b32_e32 v75, v0
	v_mov_b32_e32 v76, v0
	v_mov_b32_e32 v77, v0
	v_mov_b32_e32 v78, v0
	v_mov_b32_e32 v79, v0
	v_mov_b32_e32 v88, v0
	v_mov_b32_e32 v89, v0
	v_mov_b32_e32 v90, v0
	v_mov_b32_e32 v91, v0
	v_mov_b32_e32 v92, v0
	v_mov_b32_e32 v93, v0
	v_mov_b32_e32 v94, v0
	v_mov_b32_e32 v95, v0
	v_mov_b32_e32 v104, v0
	v_mov_b32_e32 v105, v0
	v_mov_b32_e32 v106, v0
	v_mov_b32_e32 v107, v0
	v_mov_b32_e32 v108, v0
	v_mov_b32_e32 v109, v0
	v_mov_b32_e32 v110, v0
	v_mov_b32_e32 v111, v0
	v_mov_b32_e32 v120, v0
	v_mov_b32_e32 v121, v0
	v_mov_b32_e32 v122, v0
	v_mov_b32_e32 v123, v0
	v_mov_b32_e32 v124, v0
	v_mov_b32_e32 v125, v0
	v_mov_b32_e32 v126, v0
	v_mov_b32_e32 v127, v0
	s_branch .LBB0_966
